# v25 + S5 GEMM operand LDS-DMA loads marked nt (keep the pass-1 E block L2-resident for the scan)
# baseline (speedup 1.0000x reference)
; #define PG8_STAGE(bufoff, gbase, voff) do { _Pragma("unroll") for (int _i = 0; _i < 2; ++_i) \
;         __builtin_amdgcn_global_load_lds((const unsigned*)((const char*)(gbase) + (voff)[_i]), (PG8_LAS unsigned*)(lds + (bufoff) + ldsw + _i * 8192), 16, 0, 0); } while (0)
; #define PG8_WAIT_V(n) asm volatile("s_waitcnt vmcnt(" #n ")" ::: "memory")
; template <class Epi, class Sched, bool ALIGN_EPI = false, bool SP2 = false>
; __device__ __forceinline__ void gemm_phase(PG8_LAS unsigned char* lds, const Gemm g, const Sched& S, const Epi& E, const int tid) {
;     const int wid = __builtin_amdgcn_readfirstlane(tid >> 6), lane = tid & 63, wr = wid >> 2, wc = wid & 3, fr = lane & 15, fq = lane >> 4;
;     const int K = g.K, nt = K / BK;
;     unsigned voffA[2], voffB[2];
; #pragma unroll
;     for (int i = 0; i < 2; ++i) { int R, C; stage_rc(tid * 16 + i * 8192, R, C); const int Rb = Epi::PERM ? ((R & ~31) + perm32(R & 31)) : R;
;         voffA[i] = (unsigned)(R * g.lda + C) * 2u; voffB[i] = (unsigned)(Rb * g.ldb + C) * 2u; }
;     const size_t kstep = (size_t)(BK * 2);
;     const size_t hstepA = (size_t)HALF * g.lda * 2, hstepB = (size_t)HALF * g.ldb * 2;
;     const unsigned ldsw = (unsigned)wid * 1024u;
;     const int aoff = lds_byte(wr * 64 + fr, fq * 8), boff = lds_byte(wc * 32 + fr, fq * 8);
;     ...
;     Unit cur, nxt; int ui = 0;
;     if (!S.next(0, cur)) return;
;     f32x4 acc[2][2][4][2];
; #pragma unroll
;     for (int a = 0; a < 2; ++a)
; #pragma unroll
;         for (int b = 0; b < 2; ++b)
; #pragma unroll
;             for (int m = 0; m < 4; ++m)
; #pragma unroll
;                 for (int n = 0; n < 2; ++n) acc[a][b][m][n] = (f32x4){0.f, 0.f, 0.f, 0.f};
;     bf16x8 At[4][2], B0[2][2], B1[2][2];
;     const char* cA = (const char*)g.A + (size_t)cur.pm * 2 * hstepA; const char* cB = (const char*)g.Bt + ((size_t)(cur.pm / g.grp_tiles) * g.grp_brows + (size_t)cur.pn * BM) * g.ldb * 2;
;     S.a_ready(cur);
;     if constexpr (SP2) {
;         PG8_STAGE(PG8_SB(0, 0), cB, voffB); PG8_STAGE(PG8_SB(0, 1), cB + hstepB, voffB); PG8_STAGE(PG8_SA(0, 0), cA, voffA); PG8_STAGE(PG8_SA(0, 1), cA + hstepA, voffA);
;         if (wr == 1) PG8_BAR;
;         PG8_WAIT_V(2); PG8_BAR;
;         PG8_STAGE(PG8_SB(1, 0), cB + kstep, voffB); PG8_STAGE(PG8_SA(1, 0), cA + kstep, voffA); PG8_STAGE(PG8_SB(1, 1), cB + hstepB + kstep, voffB);
;         PG8_WAIT_V(6); PG8_BAR;
.LBB0_266:
	s_or_b64 exec, exec, s[36:37]
	v_mov_b32_e32 v0, v205
	s_mov_b32 s0, s2
	v_readlane_b32 s1, v255, 0
	v_mov_b32_e32 v2, v205
	s_waitcnt lgkmcnt(0)
	s_barrier
	v_readlane_b32 s6, v255, 8
	v_add_u32_e32 v2, 0, v2
	v_add_u32_e32 v2, 0x200c8, v2
	ds_read_b64 v[2:3], v2
	v_mbcnt_lo_u32_b32 v0, -1, v0
	v_mbcnt_hi_u32_b32 v0, -1, v0
	v_lshl_add_u32 v1, s1, 6, v0
	v_readlane_b32 s0, v255, 51
	v_readlane_b32 s7, v255, 9
	s_waitcnt lgkmcnt(0)
	v_readfirstlane_b32 s12, v2
	v_readlane_b32 s1, v255, 52
	v_cndmask_b32_e64 v2, 0, 1, s[6:7]
	v_readfirstlane_b32 s13, v3
	s_lshl_b64 s[8:9], s[0:1], 24
	v_readfirstlane_b32 s0, v1
	v_cmp_ne_u32_e64 s[4:5], 1, v2
	s_andn2_b64 vcc, exec, s[6:7]
	s_cbranch_vccnz .LBB0_288
	v_lshlrev_b32_e32 v2, 4, v1
	v_add_u32_e32 v3, 0x2000, v2
	v_ashrrev_i32_e32 v4, 31, v3
	v_lshrrev_b32_e32 v4, 22, v4
	v_add_u32_e32 v4, v3, v4
	v_ashrrev_i32_e32 v4, 10, v4
	v_mul_i32_i24_e32 v5, 0x400, v4
	v_sub_u32_e32 v3, v3, v5
	v_lshrrev_b32_e32 v5, 4, v3
	v_bitop3_b32 v3, v5, v3, 32 bitop3:0x6c
	v_ashrrev_i32_e32 v5, 31, v3
	v_lshrrev_b32_e32 v5, 26, v5
	s_add_u32 s28, s12, 0x15a00000
	v_add_u32_e32 v5, v3, v5
	v_lshlrev_b32_e32 v7, 3, v4
	s_addc_u32 s29, s13, 0
	v_ashrrev_i32_e32 v6, 6, v5
	v_and_b32_e32 v7, -16, v7
	v_and_b32_e32 v5, 0xc0, v5
	s_add_u32 s1, s12, s8
	v_add_u32_e32 v7, v6, v7
	v_lshlrev_b32_e32 v4, 5, v4
	v_sub_u32_e32 v3, v3, v5
	s_addc_u32 s6, s13, s9
	v_and_b32_e32 v6, 3, v6
	s_mov_b32 s7, 0x7fffe0
	v_lshrrev_b32_e32 v8, 2, v7
	v_lshlrev_b32_e32 v9, 1, v7
	v_and_b32_e32 v4, 32, v4
	v_ashrrev_i16_sdwa v3, v254, sext(v3) dst_sel:DWORD dst_unused:UNUSED_PAD src0_sel:DWORD src1_sel:BYTE_0
	s_add_u32 s30, s1, 0xa00000
	v_and_or_b32 v6, v7, s7, v6
	v_and_b32_e32 v8, 4, v8
	v_and_b32_e32 v9, 24, v9
	v_add_u32_sdwa v3, v4, sext(v3) dst_sel:DWORD dst_unused:UNUSED_PAD src0_sel:DWORD src1_sel:WORD_0
	s_addc_u32 s31, s6, 0
	v_or3_b32 v6, v6, v8, v9
	v_lshlrev_b32_e32 v4, 1, v3
	s_movk_i32 s6, 0x180
	v_lshl_add_u32 v64, v6, 9, v4
	v_mul_lo_u32 v4, v7, s6
	v_add_lshl_u32 v66, v3, v4, 1
	v_bfe_i32 v3, v1, 27, 1
	v_lshrrev_b32_e32 v3, 22, v3
	v_add_u32_e32 v3, v2, v3
	v_and_b32_e32 v3, 0xfffffc00, v3
	v_sub_u32_e32 v2, v2, v3
	v_lshrrev_b32_e32 v3, 4, v2
	v_ashrrev_i32_e32 v5, 31, v1
	v_bitop3_b32 v2, v3, v2, 32 bitop3:0x6c
	v_lshrrev_b32_e32 v5, 26, v5
	v_ashrrev_i32_e32 v3, 31, v2
	v_add_u32_e32 v1, v1, v5
	v_lshrrev_b32_e32 v3, 26, v3
	v_ashrrev_i32_e32 v1, 6, v1
	v_add_u32_e32 v3, v2, v3
	v_lshlrev_b32_e32 v5, 3, v1
	v_ashrrev_i32_e32 v4, 6, v3
	v_and_b32_e32 v5, -16, v5
	v_and_b32_e32 v3, 0xc0, v3
	v_add_u32_e32 v5, v4, v5
	v_lshlrev_b32_e32 v1, 5, v1
	v_sub_u32_e32 v2, v2, v3
	v_and_b32_e32 v4, 3, v4
	v_lshrrev_b32_e32 v6, 2, v5
	v_lshlrev_b32_e32 v7, 1, v5
	v_and_b32_e32 v1, 32, v1
	v_ashrrev_i16_sdwa v2, v254, sext(v2) dst_sel:DWORD dst_unused:UNUSED_PAD src0_sel:DWORD src1_sel:BYTE_0
	v_and_or_b32 v4, v5, s7, v4
	v_and_b32_e32 v6, 4, v6
	v_and_b32_e32 v7, 24, v7
	v_add_u32_sdwa v1, v1, sext(v2) dst_sel:DWORD dst_unused:UNUSED_PAD src0_sel:DWORD src1_sel:WORD_0
	s_ashr_i32 s1, s0, 6
	v_or3_b32 v4, v4, v6, v7
	v_lshlrev_b32_e32 v2, 1, v1
	s_ashr_i32 s34, s0, 8
	s_lshl_b32 s35, s1, 10
	v_lshl_add_u32 v204, v4, 9, v2
	v_mul_lo_u32 v2, v5, s6
	v_readlane_b32 s6, v255, 13
	v_readlane_b32 s7, v255, 14
	s_add_u32 s26, s30, s6
	s_addc_u32 s27, s31, s7
	s_add_i32 s36, s35, 0
	s_add_i32 m0, s36, 0x10000
	v_add_lshl_u32 v68, v1, v2, 1
	global_load_lds_dwordx4 v204, s[26:27] nt
	s_add_i32 m0, s36, 0x12000
	s_add_u32 s6, s26, 0x10000
	s_addc_u32 s7, s27, 0
	s_add_i32 s37, s36, 0x14000
	global_load_lds_dwordx4 v64, s[26:27] nt
	s_mov_b32 m0, s37
	s_add_i32 s42, s36, 0x16000
	global_load_lds_dwordx4 v204, s[6:7] nt
	s_mov_b32 m0, s42
	s_nop 0
	global_load_lds_dwordx4 v64, s[6:7] nt
	v_readlane_b32 s6, v255, 22
	s_add_u32 s24, s28, s6
	v_readlane_b32 s6, v255, 20
	s_addc_u32 s25, s29, s6
	s_add_i32 s43, s36, 0x2000
	s_mov_b32 m0, s36
	s_add_u32 s6, s24, 0x18000
	global_load_lds_dwordx4 v68, s[24:25] nt
	s_mov_b32 m0, s43
	s_addc_u32 s7, s25, 0
	s_add_i32 s46, s36, 0x4000
	global_load_lds_dwordx4 v66, s[24:25] nt
	s_mov_b32 m0, s46
	s_add_i32 s47, s36, 0x6000
	global_load_lds_dwordx4 v68, s[6:7] nt
	s_mov_b32 m0, s47
	s_cmp_eq_u32 s34, 1
	global_load_lds_dwordx4 v66, s[6:7] nt
	s_cselect_b64 s[14:15], -1, 0
	s_cmp_lg_u32 s34, 1
	s_cbranch_scc1 .LBB0_269
	s_barrier
.LBB0_269:
	v_and_b32_e32 v70, 15, v0
	v_bfe_u32 v71, v0, 4, 2
	v_lshlrev_b32_e32 v1, 6, v70
	v_lshlrev_b32_e32 v0, 2, v0
	s_and_b32 s48, s1, 3
	v_lshl_or_b32 v1, v71, 4, v1
	s_lshl_b32 s1, s34, 13
	v_and_b32_e32 v0, 32, v0
	v_lshl_add_u64 v[2:3], s[26:27], 0, v[204:205]
	v_mov_b32_e32 v65, v205
	v_bitop3_b32 v10, s1, v1, v0 bitop3:0xf6
	s_lshl_b32 s1, s48, 12
	v_lshl_add_u64 v[4:5], s[26:27], 0, v[64:65]
	v_mov_b32_e32 v69, v205
	v_bitop3_b32 v72, s1, v1, v0 bitop3:0xf6
	s_add_i32 m0, s36, 0x18000
	v_lshl_add_u64 v[0:1], v[2:3], 0, s[82:83]
	v_lshl_add_u64 v[6:7], s[24:25], 0, v[68:69]
	v_mov_b32_e32 v67, v205
	s_waitcnt vmcnt(2)
	s_barrier
	global_load_lds_dwordx4 v[0:1], off nt
	v_lshl_add_u64 v[0:1], v[4:5], 0, s[82:83]
	s_add_i32 m0, s36, 0x1a000
	s_add_i32 s49, s36, 0x8000
	s_add_i32 s50, s36, 0xa000
	v_lshl_add_u64 v[8:9], s[24:25], 0, v[66:67]
	global_load_lds_dwordx4 v[0:1], off nt
	v_lshl_add_u64 v[0:1], v[6:7], 0, s[82:83]
	s_mov_b32 m0, s49
	s_add_u32 s6, s26, 0x10080
	global_load_lds_dwordx4 v[0:1], off nt
	v_lshl_add_u64 v[0:1], v[8:9], 0, s[82:83]
	s_mov_b32 m0, s50
	s_addc_u32 s7, s27, 0
	s_add_i32 s54, s36, 0x1c000
	global_load_lds_dwordx4 v[0:1], off nt
	v_lshl_add_u64 v[0:1], s[6:7], 0, v[204:205]
	s_mov_b32 m0, s54
	s_add_i32 s55, s36, 0x1e000
	global_load_lds_dwordx4 v[0:1], off nt
	v_lshl_add_u64 v[0:1], s[6:7], 0, v[64:65]
	s_mov_b32 m0, s55
	s_cmpk_lt_u32 s0, 0x100
	global_load_lds_dwordx4 v[0:1], off nt
	s_waitcnt vmcnt(6)
	v_readlane_b32 s18, v255, 43
	s_cselect_b64 s[16:17], -1, 0
	v_add_u32_e32 v73, 0, v10
	v_readlane_b32 s19, v255, 44
	v_readlane_b32 s57, v255, 21
	s_barrier
	s_branch .LBB0_272

; #define PG8_STAGE(bufoff, gbase, voff) do { _Pragma("unroll") for (int _i = 0; _i < 2; ++_i) \
;         __builtin_amdgcn_global_load_lds((const unsigned*)((const char*)(gbase) + (voff)[_i]), (PG8_LAS unsigned*)(lds + (bufoff) + ldsw + _i * 8192), 16, 0, 0); } while (0)
; #define PG8_LDA(dst, b, h) do { _Pragma("unroll") for (int m = 0; m < 4; ++m) _Pragma("unroll") for (int k = 0; k < 2; ++k) dst[m][k] = *(const PG8_LAS bf16x8*)(lds + PG8_SA(b, h) + aoff + m * 2048 + k * 1024); } while (0)
; #define PG8_LDB(dst, b, h) do { _Pragma("unroll") for (int n = 0; n < 2; ++n) _Pragma("unroll") for (int k = 0; k < 2; ++k) dst[n][k] = *(const PG8_LAS bf16x8*)(lds + PG8_SB(b, h) + boff + n * 2048 + k * 1024); } while (0)
; #define PG8_MMA(ai, bj, At, Bt) do { __builtin_amdgcn_s_setprio(1); _Pragma("unroll") for (int m = 0; m < 4; ++m) _Pragma("unroll") for (int n = 0; n < 2; ++n) _Pragma("unroll") for (int k = 0; k < 2; ++k) \
;         acc[ai][bj][m][n] = __builtin_amdgcn_mfma_f32_16x16x32_bf16(Bt[n][k], At[m][k], acc[ai][bj][m][n], 0, 0, 0); __builtin_amdgcn_s_setprio(0); } while (0)
; #define PG8_WAIT_V(n) asm volatile("s_waitcnt vmcnt(" #n ")" ::: "memory")
; #define PG8_WAIT_L(n) asm volatile("s_waitcnt lgkmcnt(" #n ")" ::: "memory")
; #define PG8_BAR __builtin_amdgcn_s_barrier()
; #define PG8_SCHED __builtin_amdgcn_sched_barrier(0)
; template <class Epi, class Sched, bool ALIGN_EPI = false, bool SP2 = false>
; __device__ __forceinline__ void gemm_phase(PG8_LAS unsigned char* lds, const Gemm g, const Sched& S, const Epi& E, const int tid) {
;     ...
;             if constexpr (SP2) {
;             PG8_LDB(B0, 0, 0); PG8_LDB(B1, 0, 1); PG8_SCHED; PG8_LDA(At, 0, 0); PG8_STAGE(PG8_SA(1, 1), a1 + hstepA, voffA);
;             PG8_WAIT_V(8); PG8_WAIT_L(0); PG8_BAR; PG8_MMA(0, 0, At, B0); PG8_MMA(0, 1, At, B1); PG8_BAR; PG8_SCHED;
;             PG8_LDA(At, 0, 1); PG8_STAGE(PG8_SB(0, 0), b2, voffB); PG8_STAGE(PG8_SB(0, 1), b2 + hstepB, voffB); PG8_STAGE(PG8_SA(0, 0), a2, voffA);
;             PG8_WAIT_V(8); PG8_WAIT_L(0); PG8_BAR; PG8_MMA(1, 0, At, B0); PG8_MMA(1, 1, At, B1); PG8_BAR; PG8_SCHED;
;             PG8_LDB(B0, 1, 0); PG8_LDB(B1, 1, 1); PG8_SCHED; PG8_LDA(At, 1, 0); PG8_STAGE(PG8_SA(0, 1), a2 + hstepA, voffA);
;             PG8_WAIT_V(8); PG8_WAIT_L(0); PG8_BAR; PG8_MMA(0, 0, At, B0); PG8_MMA(0, 1, At, B1); PG8_BAR; PG8_SCHED;
.LBB0_282:
	s_add_i32 s60, 0, 0x10000
	v_add_u32_e32 v132, s60, v72
	ds_read_b128 v[0:3], v132
	ds_read_b128 v[4:7], v132 offset:1024
	ds_read_b128 v[8:11], v132 offset:2048
	ds_read_b128 v[12:15], v132 offset:3072
	s_add_u32 s58, s24, 0x18080
	s_addc_u32 s59, s25, 0
	s_add_i32 s61, s36, 0xc000
	v_lshl_add_u64 v[48:49], s[58:59], 0, v[68:69]
	s_mov_b32 m0, s61
	s_add_i32 s21, s36, 0xe000
	ds_read_b128 v[16:19], v73
	ds_read_b128 v[20:23], v73 offset:1024
	ds_read_b128 v[24:27], v73 offset:2048
	ds_read_b128 v[28:31], v73 offset:3072
	ds_read_b128 v[32:35], v73 offset:4096
	ds_read_b128 v[36:39], v73 offset:5120
	ds_read_b128 v[40:43], v73 offset:6144
	ds_read_b128 v[44:47], v73 offset:7168
	global_load_lds_dwordx4 v[48:49], off nt
	v_lshl_add_u64 v[48:49], s[58:59], 0, v[66:67]
	s_mov_b32 m0, s21
	s_nop 0
	global_load_lds_dwordx4 v[48:49], off nt
	s_waitcnt vmcnt(8)
	s_waitcnt lgkmcnt(0)
	s_barrier
	s_setprio 1
	s_waitcnt lgkmcnt(0)
	v_mfma_f32_16x16x32_bf16 v[48:51], v[0:3], v[16:19], 0
	v_mfma_f32_16x16x32_bf16 v[16:19], v[8:11], v[16:19], 0
	v_mfma_f32_16x16x32_bf16 v[48:51], v[4:7], v[20:23], v[48:51]
	v_mfma_f32_16x16x32_bf16 v[16:19], v[12:15], v[20:23], v[16:19]
	v_mfma_f32_16x16x32_bf16 v[20:23], v[0:3], v[24:27], 0
	v_mfma_f32_16x16x32_bf16 v[24:27], v[8:11], v[24:27], 0
	v_mfma_f32_16x16x32_bf16 v[20:23], v[4:7], v[28:31], v[20:23]
	v_mfma_f32_16x16x32_bf16 v[24:27], v[12:15], v[28:31], v[24:27]
	v_mfma_f32_16x16x32_bf16 v[28:31], v[0:3], v[32:35], 0
	v_mfma_f32_16x16x32_bf16 v[32:35], v[8:11], v[32:35], 0
	v_mfma_f32_16x16x32_bf16 v[28:31], v[4:7], v[36:39], v[28:31]
	v_mfma_f32_16x16x32_bf16 v[32:35], v[12:15], v[36:39], v[32:35]
	v_mfma_f32_16x16x32_bf16 v[36:39], v[0:3], v[40:43], 0
	v_mfma_f32_16x16x32_bf16 v[40:43], v[8:11], v[40:43], 0
	v_mfma_f32_16x16x32_bf16 v[36:39], v[4:7], v[44:47], v[36:39]
	v_mfma_f32_16x16x32_bf16 v[40:43], v[12:15], v[44:47], v[40:43]
	s_setprio 0
	s_setprio 1
	s_setprio 0
	s_barrier
	s_add_i32 s60, s60, s35
	v_lshl_add_u64 v[122:123], s[26:27], 0, v[204:205]
	s_add_i32 s58, s60, 0x2000
	v_lshl_add_u64 v[90:91], v[122:123], 0, s[84:85]
	s_mov_b32 m0, s60
	v_lshl_add_u64 v[124:125], s[26:27], 0, v[64:65]
	s_add_u32 s62, s26, 0x10100
	ds_read_b128 v[44:47], v73 offset:16384
	ds_read_b128 v[52:55], v73 offset:17408
	ds_read_b128 v[56:59], v73 offset:18432
	ds_read_b128 v[60:63], v73 offset:19456
	ds_read_b128 v[74:77], v73 offset:20480
	ds_read_b128 v[78:81], v73 offset:21504
	ds_read_b128 v[82:85], v73 offset:22528
	ds_read_b128 v[86:89], v73 offset:23552
	global_load_lds_dwordx4 v[90:91], off nt
	v_lshl_add_u64 v[90:91], v[124:125], 0, s[84:85]
	s_mov_b32 m0, s58
	s_addc_u32 s63, s27, 0
	global_load_lds_dwordx4 v[90:91], off nt
	v_lshl_add_u64 v[90:91], s[62:63], 0, v[204:205]
	s_mov_b32 m0, s37
	v_lshl_add_u64 v[126:127], s[24:25], 0, v[68:69]
	global_load_lds_dwordx4 v[90:91], off nt
	v_lshl_add_u64 v[90:91], s[62:63], 0, v[64:65]
	s_mov_b32 m0, s42
	v_lshl_add_u64 v[128:129], s[24:25], 0, v[66:67]
	global_load_lds_dwordx4 v[90:91], off nt
	v_lshl_add_u64 v[90:91], v[126:127], 0, s[84:85]
	s_mov_b32 m0, s36
	s_nop 0
	global_load_lds_dwordx4 v[90:91], off nt
	v_lshl_add_u64 v[90:91], v[128:129], 0, s[84:85]
	s_mov_b32 m0, s43
	s_nop 0
	global_load_lds_dwordx4 v[90:91], off nt
	s_waitcnt vmcnt(8)
	s_waitcnt lgkmcnt(0)
	s_barrier
	s_setprio 1
	s_waitcnt lgkmcnt(0)
	v_mfma_f32_16x16x32_bf16 v[90:93], v[0:3], v[44:47], 0
	v_mfma_f32_16x16x32_bf16 v[44:47], v[8:11], v[44:47], 0
	v_mfma_f32_16x16x32_bf16 v[90:93], v[4:7], v[52:55], v[90:93]
	v_mfma_f32_16x16x32_bf16 v[44:47], v[12:15], v[52:55], v[44:47]
	v_mfma_f32_16x16x32_bf16 v[52:55], v[0:3], v[56:59], 0
	v_mfma_f32_16x16x32_bf16 v[56:59], v[8:11], v[56:59], 0
	v_mfma_f32_16x16x32_bf16 v[52:55], v[4:7], v[60:63], v[52:55]
	v_mfma_f32_16x16x32_bf16 v[56:59], v[12:15], v[60:63], v[56:59]
	v_mfma_f32_16x16x32_bf16 v[60:63], v[0:3], v[74:77], 0
	v_mfma_f32_16x16x32_bf16 v[0:3], v[0:3], v[82:85], 0
	v_mfma_f32_16x16x32_bf16 v[60:63], v[4:7], v[78:81], v[60:63]
	v_mfma_f32_16x16x32_bf16 v[0:3], v[4:7], v[86:89], v[0:3]
	v_mfma_f32_16x16x32_bf16 v[4:7], v[8:11], v[82:85], 0
	v_mfma_f32_16x16x32_bf16 v[74:77], v[8:11], v[74:77], 0
	v_mfma_f32_16x16x32_bf16 v[4:7], v[12:15], v[86:89], v[4:7]
	v_mfma_f32_16x16x32_bf16 v[74:77], v[12:15], v[78:81], v[74:77]
	s_setprio 0
	s_setprio 1
	s_setprio 0
	s_barrier
	s_add_i32 s59, 0, 0x18000
	v_add_u32_e32 v133, s59, v72
	ds_read_b128 v[8:11], v133
	ds_read_b128 v[12:15], v133 offset:1024
	ds_read_b128 v[78:81], v133 offset:2048
	ds_read_b128 v[82:85], v133 offset:3072
	s_add_u32 s62, s24, 0x18100
	s_addc_u32 s63, s25, 0
	s_mov_b32 m0, s46
	v_lshl_add_u64 v[130:131], s[62:63], 0, v[68:69]
	ds_read_b128 v[86:89], v73 offset:32768
	ds_read_b128 v[94:97], v73 offset:33792
	ds_read_b128 v[98:101], v73 offset:34816
	ds_read_b128 v[102:105], v73 offset:35840
	ds_read_b128 v[106:109], v73 offset:36864
	ds_read_b128 v[110:113], v73 offset:37888
	ds_read_b128 v[114:117], v73 offset:38912
	ds_read_b128 v[118:121], v73 offset:39936
	global_load_lds_dwordx4 v[130:131], off nt
	v_lshl_add_u64 v[130:131], s[62:63], 0, v[66:67]
	s_mov_b32 m0, s47
	s_nop 0
	global_load_lds_dwordx4 v[130:131], off nt
	s_waitcnt vmcnt(8)
	s_waitcnt lgkmcnt(0)
	s_barrier
; #define PG8_STAGE(bufoff, gbase, voff) do { _Pragma("unroll") for (int _i = 0; _i < 2; ++_i) \
;         __builtin_amdgcn_global_load_lds((const unsigned*)((const char*)(gbase) + (voff)[_i]), (PG8_LAS unsigned*)(lds + (bufoff) + ldsw + _i * 8192), 16, 0, 0); } while (0)
; #define PG8_LDA(dst, b, h) do { _Pragma("unroll") for (int m = 0; m < 4; ++m) _Pragma("unroll") for (int k = 0; k < 2; ++k) dst[m][k] = *(const PG8_LAS bf16x8*)(lds + PG8_SA(b, h) + aoff + m * 2048 + k * 1024); } while (0)
; #define PG8_LDB(dst, b, h) do { _Pragma("unroll") for (int n = 0; n < 2; ++n) _Pragma("unroll") for (int k = 0; k < 2; ++k) dst[n][k] = *(const PG8_LAS bf16x8*)(lds + PG8_SB(b, h) + boff + n * 2048 + k * 1024); } while (0)
; #define PG8_MMA(ai, bj, At, Bt) do { __builtin_amdgcn_s_setprio(1); _Pragma("unroll") for (int m = 0; m < 4; ++m) _Pragma("unroll") for (int n = 0; n < 2; ++n) _Pragma("unroll") for (int k = 0; k < 2; ++k) \
;         acc[ai][bj][m][n] = __builtin_amdgcn_mfma_f32_16x16x32_bf16(Bt[n][k], At[m][k], acc[ai][bj][m][n], 0, 0, 0); __builtin_amdgcn_s_setprio(0); } while (0)
; #define PG8_WAIT_V(n) asm volatile("s_waitcnt vmcnt(" #n ")" ::: "memory")
; #define PG8_WAIT_L(n) asm volatile("s_waitcnt lgkmcnt(" #n ")" ::: "memory")
; #define PG8_BAR __builtin_amdgcn_s_barrier()
; #define PG8_SCHED __builtin_amdgcn_sched_barrier(0)
; template <class Epi, class Sched, bool ALIGN_EPI = false, bool SP2 = false>
; __device__ __forceinline__ void gemm_phase(PG8_LAS unsigned char* lds, const Gemm g, const Sched& S, const Epi& E, const int tid) {
;     ...
;             PG8_WAIT_V(8); PG8_WAIT_L(0); PG8_BAR; PG8_MMA(1, 0, At, B0); PG8_MMA(1, 1, At, B1); PG8_BAR; PG8_SCHED;
;             PG8_LDB(B0, 1, 0); PG8_LDB(B1, 1, 1); PG8_SCHED; PG8_LDA(At, 1, 0); PG8_STAGE(PG8_SA(0, 1), a2 + hstepA, voffA);
;             PG8_WAIT_V(8); PG8_WAIT_L(0); PG8_BAR; PG8_MMA(0, 0, At, B0); PG8_MMA(0, 1, At, B1); PG8_BAR; PG8_SCHED;
;             PG8_LDA(At, 1, 1); PG8_STAGE(PG8_SB(1, 0), b3, voffB); PG8_STAGE(PG8_SB(1, 1), b3 + hstepB, voffB); PG8_STAGE(PG8_SA(1, 0), a3, voffA);
;             PG8_WAIT_V(8); PG8_WAIT_L(0); PG8_BAR; PG8_MMA(1, 0, At, B0); PG8_MMA(1, 1, At, B1); PG8_BAR; PG8_SCHED;
	s_setprio 1
	s_waitcnt lgkmcnt(0)
	v_mfma_f32_16x16x32_bf16 v[48:51], v[8:11], v[86:89], v[48:51]
	v_mfma_f32_16x16x32_bf16 v[16:19], v[78:81], v[86:89], v[16:19]
	v_mfma_f32_16x16x32_bf16 v[20:23], v[8:11], v[98:101], v[20:23]
	v_mfma_f32_16x16x32_bf16 v[24:27], v[78:81], v[98:101], v[24:27]
	v_mfma_f32_16x16x32_bf16 v[28:31], v[8:11], v[106:109], v[28:31]
	v_mfma_f32_16x16x32_bf16 v[32:35], v[78:81], v[106:109], v[32:35]
	v_mfma_f32_16x16x32_bf16 v[36:39], v[8:11], v[114:117], v[36:39]
	v_mfma_f32_16x16x32_bf16 v[40:43], v[78:81], v[114:117], v[40:43]
	v_mfma_f32_16x16x32_bf16 v[48:51], v[12:15], v[94:97], v[48:51]
	v_mfma_f32_16x16x32_bf16 v[16:19], v[82:85], v[94:97], v[16:19]
	v_mfma_f32_16x16x32_bf16 v[20:23], v[12:15], v[102:105], v[20:23]
	v_mfma_f32_16x16x32_bf16 v[24:27], v[82:85], v[102:105], v[24:27]
	v_mfma_f32_16x16x32_bf16 v[28:31], v[12:15], v[110:113], v[28:31]
	v_mfma_f32_16x16x32_bf16 v[32:35], v[82:85], v[110:113], v[32:35]
	v_mfma_f32_16x16x32_bf16 v[36:39], v[12:15], v[118:121], v[36:39]
	v_mfma_f32_16x16x32_bf16 v[40:43], v[82:85], v[118:121], v[40:43]
	s_setprio 0
	s_setprio 1
	s_setprio 0
	s_barrier
	s_add_i32 s62, s59, s35
	s_add_i32 s59, s62, 0x2000
	v_lshl_add_u64 v[122:123], v[122:123], 0, s[94:95]
	s_mov_b32 m0, s62
	s_add_u32 s26, s26, 0x10180
	ds_read_b128 v[86:89], v73 offset:49152
	ds_read_b128 v[94:97], v73 offset:50176
	ds_read_b128 v[98:101], v73 offset:51200
	ds_read_b128 v[102:105], v73 offset:52224
	ds_read_b128 v[106:109], v73 offset:53248
	ds_read_b128 v[110:113], v73 offset:54272
	ds_read_b128 v[114:117], v73 offset:55296
	ds_read_b128 v[118:121], v73 offset:56320
	global_load_lds_dwordx4 v[122:123], off nt
	v_lshl_add_u64 v[122:123], v[124:125], 0, s[94:95]
	s_mov_b32 m0, s59
	s_addc_u32 s27, s27, 0
	global_load_lds_dwordx4 v[122:123], off nt
	v_lshl_add_u64 v[122:123], s[26:27], 0, v[204:205]
	s_mov_b32 m0, s54
	s_nop 0
	global_load_lds_dwordx4 v[122:123], off nt
	v_lshl_add_u64 v[122:123], s[26:27], 0, v[64:65]
	s_mov_b32 m0, s55
	s_nop 0
	global_load_lds_dwordx4 v[122:123], off nt
	v_lshl_add_u64 v[122:123], v[126:127], 0, s[94:95]
	s_mov_b32 m0, s49
	s_nop 0
	global_load_lds_dwordx4 v[122:123], off nt
	v_lshl_add_u64 v[122:123], v[128:129], 0, s[94:95]
	s_mov_b32 m0, s50
	s_nop 0
	global_load_lds_dwordx4 v[122:123], off nt
	s_waitcnt vmcnt(8)
	s_waitcnt lgkmcnt(0)
	s_barrier
	s_setprio 1
	s_waitcnt lgkmcnt(0)
	v_mfma_f32_16x16x32_bf16 v[44:47], v[78:81], v[86:89], v[44:47]
	v_mfma_f32_16x16x32_bf16 v[52:55], v[8:11], v[98:101], v[52:55]
	v_mfma_f32_16x16x32_bf16 v[56:59], v[78:81], v[98:101], v[56:59]
	v_mfma_f32_16x16x32_bf16 v[60:63], v[8:11], v[106:109], v[60:63]
	v_mfma_f32_16x16x32_bf16 v[0:3], v[8:11], v[114:117], v[0:3]
	v_mfma_f32_16x16x32_bf16 v[4:7], v[78:81], v[114:117], v[4:7]
	v_mfma_f32_16x16x32_bf16 v[90:93], v[8:11], v[86:89], v[90:93]
	v_mfma_f32_16x16x32_bf16 v[44:47], v[82:85], v[94:97], v[44:47]
	v_mfma_f32_16x16x32_bf16 v[52:55], v[12:15], v[102:105], v[52:55]
	v_mfma_f32_16x16x32_bf16 v[56:59], v[82:85], v[102:105], v[56:59]
	v_mfma_f32_16x16x32_bf16 v[60:63], v[12:15], v[110:113], v[60:63]
	v_mfma_f32_16x16x32_bf16 v[74:77], v[78:81], v[106:109], v[74:77]
	v_mfma_f32_16x16x32_bf16 v[0:3], v[12:15], v[118:121], v[0:3]
	v_mfma_f32_16x16x32_bf16 v[4:7], v[82:85], v[118:121], v[4:7]
	v_mfma_f32_16x16x32_bf16 v[90:93], v[12:15], v[94:97], v[90:93]
	v_mfma_f32_16x16x32_bf16 v[74:77], v[82:85], v[110:113], v[74:77]
	s_setprio 0
	s_setprio 1
	s_setprio 0
	s_barrier
	ds_read_b128 v[8:11], v132
	ds_read_b128 v[12:15], v132 offset:1024
	ds_read_b128 v[78:81], v132 offset:2048
	ds_read_b128 v[82:85], v132 offset:3072
	s_add_u32 s24, s24, 0x18180
	s_addc_u32 s25, s25, 0
	s_mov_b32 m0, s61
	v_lshl_add_u64 v[122:123], s[24:25], 0, v[68:69]
	ds_read_b128 v[86:89], v73
	ds_read_b128 v[94:97], v73 offset:1024
	ds_read_b128 v[98:101], v73 offset:2048
	ds_read_b128 v[102:105], v73 offset:3072
	ds_read_b128 v[106:109], v73 offset:4096
	ds_read_b128 v[110:113], v73 offset:5120
	ds_read_b128 v[114:117], v73 offset:6144
	ds_read_b128 v[118:121], v73 offset:7168
	global_load_lds_dwordx4 v[122:123], off nt
	v_lshl_add_u64 v[122:123], s[24:25], 0, v[66:67]
	s_mov_b32 m0, s21
	s_nop 0
	global_load_lds_dwordx4 v[122:123], off nt
	s_waitcnt vmcnt(8)
	s_waitcnt lgkmcnt(0)
	s_barrier
	s_setprio 1
	s_waitcnt lgkmcnt(0)
	v_mfma_f32_16x16x32_bf16 v[28:31], v[8:11], v[106:109], v[28:31]
	v_mfma_f32_16x16x32_bf16 v[48:51], v[8:11], v[86:89], v[48:51]
	v_mfma_f32_16x16x32_bf16 v[16:19], v[78:81], v[86:89], v[16:19]
	v_mfma_f32_16x16x32_bf16 v[86:89], v[12:15], v[110:113], v[28:31]
	v_mfma_f32_16x16x32_bf16 v[28:31], v[78:81], v[106:109], v[32:35]
	v_mfma_f32_16x16x32_bf16 v[32:35], v[82:85], v[110:113], v[28:31]
	v_mfma_f32_16x16x32_bf16 v[28:31], v[8:11], v[114:117], v[36:39]
	v_mfma_f32_16x16x32_bf16 v[48:51], v[12:15], v[94:97], v[48:51]
	v_mfma_f32_16x16x32_bf16 v[16:19], v[82:85], v[94:97], v[16:19]
	v_mfma_f32_16x16x32_bf16 v[20:23], v[8:11], v[98:101], v[20:23]
	v_mfma_f32_16x16x32_bf16 v[24:27], v[78:81], v[98:101], v[24:27]
	v_mfma_f32_16x16x32_bf16 v[94:97], v[12:15], v[118:121], v[28:31]
	v_mfma_f32_16x16x32_bf16 v[28:31], v[78:81], v[114:117], v[40:43]
	v_mfma_f32_16x16x32_bf16 v[20:23], v[12:15], v[102:105], v[20:23]
	v_mfma_f32_16x16x32_bf16 v[24:27], v[82:85], v[102:105], v[24:27]
	v_mfma_f32_16x16x32_bf16 v[40:43], v[82:85], v[118:121], v[28:31]
	s_setprio 0
	s_setprio 1
	s_setprio 0
	s_barrier
; #define PG8_STAGE(bufoff, gbase, voff) do { _Pragma("unroll") for (int _i = 0; _i < 2; ++_i) \
;         __builtin_amdgcn_global_load_lds((const unsigned*)((const char*)(gbase) + (voff)[_i]), (PG8_LAS unsigned*)(lds + (bufoff) + ldsw + _i * 8192), 16, 0, 0); } while (0)
; #define PG8_LDA(dst, b, h) do { _Pragma("unroll") for (int m = 0; m < 4; ++m) _Pragma("unroll") for (int k = 0; k < 2; ++k) dst[m][k] = *(const PG8_LAS bf16x8*)(lds + PG8_SA(b, h) + aoff + m * 2048 + k * 1024); } while (0)
; #define PG8_LDB(dst, b, h) do { _Pragma("unroll") for (int n = 0; n < 2; ++n) _Pragma("unroll") for (int k = 0; k < 2; ++k) dst[n][k] = *(const PG8_LAS bf16x8*)(lds + PG8_SB(b, h) + boff + n * 2048 + k * 1024); } while (0)
; #define PG8_WAIT_V(n) asm volatile("s_waitcnt vmcnt(" #n ")" ::: "memory")
; template <class Epi, class Sched, bool ALIGN_EPI = false, bool SP2 = false>
; __device__ __forceinline__ void gemm_phase(PG8_LAS unsigned char* lds, const Gemm g, const Sched& S, const Epi& E, const int tid) {
;     ...
;             const char* a2 = last ? nA : cA + (size_t)(t + 2) * kstep; const char* b2 = last ? nB : cB + (size_t)(t + 2) * kstep;
;             const char* a3 = a2 + kstep; const char* b3 = b2 + kstep;
;             if (last && has_next) S.a_ready(nxt);
;             if constexpr (SP2) {
;             PG8_LDB(B0, 0, 0); PG8_LDB(B1, 0, 1); PG8_SCHED; PG8_LDA(At, 0, 0); PG8_STAGE(PG8_SA(1, 1), a1 + hstepA, voffA);
;             PG8_WAIT_V(8); PG8_WAIT_L(0); PG8_BAR; PG8_MMA(0, 0, At, B0); PG8_MMA(0, 1, At, B1); PG8_BAR; PG8_SCHED;
;             PG8_LDA(At, 0, 1); PG8_STAGE(PG8_SB(0, 0), b2, voffB); PG8_STAGE(PG8_SB(0, 1), b2 + hstepB, voffB); PG8_STAGE(PG8_SA(0, 0), a2, voffA);
;             PG8_WAIT_V(8); PG8_WAIT_L(0); PG8_BAR; PG8_MMA(1, 0, At, B0); PG8_MMA(1, 1, At, B1); PG8_BAR; PG8_SCHED;
;             PG8_LDB(B0, 1, 0); PG8_LDB(B1, 1, 1); PG8_SCHED; PG8_LDA(At, 1, 0); PG8_STAGE(PG8_SA(0, 1), a2 + hstepA, voffA);
;             PG8_WAIT_V(8); PG8_WAIT_L(0); PG8_BAR; PG8_MMA(0, 0, At, B0); PG8_MMA(0, 1, At, B1); PG8_BAR; PG8_SCHED;
;             PG8_LDA(At, 1, 1); PG8_STAGE(PG8_SB(1, 0), b3, voffB); PG8_STAGE(PG8_SB(1, 1), b3 + hstepB, voffB); PG8_STAGE(PG8_SA(1, 0), a3, voffA);
;             PG8_WAIT_V(8); PG8_WAIT_L(0); PG8_BAR; PG8_MMA(1, 0, At, B0); PG8_MMA(1, 1, At, B1); PG8_BAR; PG8_SCHED;
;     ...
;         if constexpr (ALIGN_EPI) { if (wr == 0) PG8_BAR; }
	s_mov_b32 m0, s60
	v_lshl_add_u64 v[134:135], s[22:23], 0, v[204:205]
	s_add_u32 s24, s22, 0x10000
	ds_read_b128 v[28:31], v73 offset:16384
	ds_read_b128 v[36:39], v73 offset:17408
	ds_read_b128 v[98:101], v73 offset:18432
	ds_read_b128 v[102:105], v73 offset:19456
	ds_read_b128 v[106:109], v73 offset:20480
	ds_read_b128 v[110:113], v73 offset:21504
	ds_read_b128 v[114:117], v73 offset:22528
	ds_read_b128 v[118:121], v73 offset:23552
	global_load_lds_dwordx4 v[134:135], off nt
	v_lshl_add_u64 v[136:137], s[22:23], 0, v[64:65]
	s_mov_b32 m0, s58
	s_addc_u32 s25, s23, 0
	global_load_lds_dwordx4 v[136:137], off nt
	v_lshl_add_u64 v[122:123], s[24:25], 0, v[204:205]
	s_mov_b32 m0, s37
	v_lshl_add_u64 v[138:139], s[0:1], 0, v[68:69]
	global_load_lds_dwordx4 v[122:123], off nt
	v_lshl_add_u64 v[122:123], s[24:25], 0, v[64:65]
	s_mov_b32 m0, s42
	v_lshl_add_u64 v[140:141], s[0:1], 0, v[66:67]
	global_load_lds_dwordx4 v[122:123], off nt
	s_mov_b32 m0, s36
	s_nop 0
	global_load_lds_dwordx4 v[138:139], off nt
	s_mov_b32 m0, s43
	s_nop 0
	global_load_lds_dwordx4 v[140:141], off nt
	s_waitcnt vmcnt(8)
	s_waitcnt lgkmcnt(0)
	s_barrier
	s_setprio 1
	s_waitcnt lgkmcnt(0)
	v_mfma_f32_16x16x32_bf16 v[90:93], v[8:11], v[28:31], v[90:93]
	v_mfma_f32_16x16x32_bf16 v[28:31], v[78:81], v[28:31], v[44:47]
	v_mfma_f32_16x16x32_bf16 v[44:47], v[82:85], v[36:39], v[28:31]
	v_mfma_f32_16x16x32_bf16 v[28:31], v[8:11], v[98:101], v[52:55]
	v_mfma_f32_16x16x32_bf16 v[52:55], v[12:15], v[102:105], v[28:31]
	v_mfma_f32_16x16x32_bf16 v[28:31], v[78:81], v[98:101], v[56:59]
	v_mfma_f32_16x16x32_bf16 v[98:101], v[82:85], v[102:105], v[28:31]
	v_mfma_f32_16x16x32_bf16 v[28:31], v[8:11], v[106:109], v[60:63]
	v_mfma_f32_16x16x32_bf16 v[0:3], v[8:11], v[114:117], v[0:3]
	v_mfma_f32_16x16x32_bf16 v[102:105], v[12:15], v[110:113], v[28:31]
	v_mfma_f32_16x16x32_bf16 v[28:31], v[78:81], v[106:109], v[74:77]
	v_mfma_f32_16x16x32_bf16 v[106:109], v[12:15], v[118:121], v[0:3]
	v_mfma_f32_16x16x32_bf16 v[0:3], v[78:81], v[114:117], v[4:7]
	v_mfma_f32_16x16x32_bf16 v[90:93], v[12:15], v[36:39], v[90:93]
	v_mfma_f32_16x16x32_bf16 v[74:77], v[82:85], v[110:113], v[28:31]
	v_mfma_f32_16x16x32_bf16 v[78:81], v[82:85], v[118:121], v[0:3]
	s_setprio 0
	s_setprio 1
	s_setprio 0
	s_barrier
	ds_read_b128 v[82:85], v133
	ds_read_b128 v[110:113], v133 offset:1024
	ds_read_b128 v[114:117], v133 offset:2048
	ds_read_b128 v[118:121], v133 offset:3072
	s_add_u32 s24, s0, 0x18000
	s_addc_u32 s25, s1, 0
	s_mov_b32 m0, s46
	v_lshl_add_u64 v[28:29], s[24:25], 0, v[68:69]
	ds_read_b128 v[0:3], v73 offset:32768
	ds_read_b128 v[4:7], v73 offset:33792
	ds_read_b128 v[8:11], v73 offset:34816
	ds_read_b128 v[12:15], v73 offset:35840
	ds_read_b128 v[56:59], v73 offset:36864
	ds_read_b128 v[60:63], v73 offset:37888
	ds_read_b128 v[122:125], v73 offset:38912
	ds_read_b128 v[126:129], v73 offset:39936
	global_load_lds_dwordx4 v[28:29], off nt
	v_lshl_add_u64 v[28:29], s[24:25], 0, v[66:67]
	s_mov_b32 m0, s47
	s_nop 0
	global_load_lds_dwordx4 v[28:29], off nt
	s_waitcnt vmcnt(8)
	s_waitcnt lgkmcnt(0)
	s_barrier
	s_setprio 1
	s_waitcnt lgkmcnt(0)
	v_mfma_f32_16x16x32_bf16 v[28:31], v[82:85], v[0:3], v[48:51]
	v_mfma_f32_16x16x32_bf16 v[0:3], v[114:117], v[0:3], v[16:19]
	v_mfma_f32_16x16x32_bf16 v[36:39], v[118:121], v[4:7], v[0:3]
	v_mfma_f32_16x16x32_bf16 v[0:3], v[82:85], v[8:11], v[20:23]
	v_mfma_f32_16x16x32_bf16 v[16:19], v[110:113], v[12:15], v[0:3]
	v_mfma_f32_16x16x32_bf16 v[0:3], v[114:117], v[8:11], v[24:27]
	v_mfma_f32_16x16x32_bf16 v[20:23], v[118:121], v[12:15], v[0:3]
	v_mfma_f32_16x16x32_bf16 v[0:3], v[82:85], v[56:59], v[86:89]
	v_mfma_f32_16x16x32_bf16 v[8:11], v[110:113], v[60:63], v[0:3]
	v_mfma_f32_16x16x32_bf16 v[0:3], v[114:117], v[56:59], v[32:35]
	v_mfma_f32_16x16x32_bf16 v[28:31], v[110:113], v[4:7], v[28:31]
	v_mfma_f32_16x16x32_bf16 v[12:15], v[118:121], v[60:63], v[0:3]
	v_mfma_f32_16x16x32_bf16 v[0:3], v[82:85], v[122:125], v[94:97]
	v_mfma_f32_16x16x32_bf16 v[4:7], v[114:117], v[122:125], v[40:43]
	v_mfma_f32_16x16x32_bf16 v[0:3], v[110:113], v[126:129], v[0:3]
	v_mfma_f32_16x16x32_bf16 v[4:7], v[118:121], v[126:129], v[4:7]
	s_setprio 0
	s_setprio 1
	s_setprio 0
	s_barrier
	s_mov_b32 m0, s62
	v_lshl_add_u64 v[48:49], v[134:135], 0, s[82:83]
	s_add_u32 s24, s22, 0x10080
	ds_read_b128 v[24:27], v73 offset:49152
	ds_read_b128 v[32:35], v73 offset:50176
	ds_read_b128 v[40:43], v73 offset:51200
	ds_read_b128 v[86:89], v73 offset:52224
	ds_read_b128 v[94:97], v73 offset:53248
	ds_read_b128 v[122:125], v73 offset:54272
	ds_read_b128 v[126:129], v73 offset:55296
	ds_read_b128 v[130:133], v73 offset:56320
	global_load_lds_dwordx4 v[48:49], off nt
	v_lshl_add_u64 v[48:49], v[136:137], 0, s[82:83]
	s_mov_b32 m0, s59
	s_addc_u32 s25, s23, 0
	global_load_lds_dwordx4 v[48:49], off nt
	v_lshl_add_u64 v[48:49], s[24:25], 0, v[204:205]
	s_mov_b32 m0, s54
	s_nop 0
	global_load_lds_dwordx4 v[48:49], off nt
	v_lshl_add_u64 v[48:49], s[24:25], 0, v[64:65]
	s_mov_b32 m0, s55
	s_nop 0
	global_load_lds_dwordx4 v[48:49], off nt
	v_lshl_add_u64 v[48:49], v[138:139], 0, s[82:83]
	s_mov_b32 m0, s49
	s_nop 0
	global_load_lds_dwordx4 v[48:49], off nt
	v_lshl_add_u64 v[48:49], v[140:141], 0, s[82:83]
	s_mov_b32 m0, s50
	s_nop 0
	global_load_lds_dwordx4 v[48:49], off nt
	s_waitcnt vmcnt(8)
	s_waitcnt lgkmcnt(0)
	s_barrier
	s_setprio 1
	s_waitcnt lgkmcnt(0)
	v_mfma_f32_16x16x32_bf16 v[48:51], v[82:85], v[24:27], v[90:93]
	v_mfma_f32_16x16x32_bf16 v[24:27], v[114:117], v[24:27], v[44:47]
	v_mfma_f32_16x16x32_bf16 v[60:63], v[118:121], v[32:35], v[24:27]
	v_mfma_f32_16x16x32_bf16 v[24:27], v[82:85], v[40:43], v[52:55]
	v_mfma_f32_16x16x32_bf16 v[56:59], v[110:113], v[32:35], v[48:51]
	v_mfma_f32_16x16x32_bf16 v[48:51], v[110:113], v[86:89], v[24:27]
	v_mfma_f32_16x16x32_bf16 v[24:27], v[114:117], v[40:43], v[98:101]
	v_mfma_f32_16x16x32_bf16 v[52:55], v[118:121], v[86:89], v[24:27]
	v_mfma_f32_16x16x32_bf16 v[24:27], v[82:85], v[94:97], v[102:105]
	v_mfma_f32_16x16x32_bf16 v[40:43], v[110:113], v[122:125], v[24:27]
	v_mfma_f32_16x16x32_bf16 v[24:27], v[114:117], v[94:97], v[74:77]
	v_mfma_f32_16x16x32_bf16 v[44:47], v[118:121], v[122:125], v[24:27]
	v_mfma_f32_16x16x32_bf16 v[24:27], v[82:85], v[126:129], v[106:109]
	v_mfma_f32_16x16x32_bf16 v[32:35], v[114:117], v[126:129], v[78:81]
	v_mfma_f32_16x16x32_bf16 v[24:27], v[110:113], v[130:133], v[24:27]
	v_mfma_f32_16x16x32_bf16 v[32:35], v[118:121], v[130:133], v[32:35]
	s_setprio 0
	s_setprio 1
	s_setprio 0
	s_barrier
	s_andn2_b64 vcc, exec, s[16:17]
	s_cbranch_vccnz .LBB0_284
	s_barrier

; #define PG8_STAGE(bufoff, gbase, voff) do { _Pragma("unroll") for (int _i = 0; _i < 2; ++_i) \
;         __builtin_amdgcn_global_load_lds((const unsigned*)((const char*)(gbase) + (voff)[_i]), (PG8_LAS unsigned*)(lds + (bufoff) + ldsw + _i * 8192), 16, 0, 0); } while (0)
; #define PG8_WAIT_V(n) asm volatile("s_waitcnt vmcnt(" #n ")" ::: "memory")
; template <class Epi, class Sched, bool ALIGN_EPI = false, bool SP2 = false>
; __device__ __forceinline__ void gemm_phase(PG8_LAS unsigned char* lds, const Gemm g, const Sched& S, const Epi& E, const int tid) {
;     const int wid = __builtin_amdgcn_readfirstlane(tid >> 6), lane = tid & 63, wr = wid >> 2, wc = wid & 3, fr = lane & 15, fq = lane >> 4;
;     const int K = g.K, nt = K / BK;
;     unsigned voffA[2], voffB[2];
; #pragma unroll
;     for (int i = 0; i < 2; ++i) { int R, C; stage_rc(tid * 16 + i * 8192, R, C); const int Rb = Epi::PERM ? ((R & ~31) + perm32(R & 31)) : R;
;         voffA[i] = (unsigned)(R * g.lda + C) * 2u; voffB[i] = (unsigned)(Rb * g.ldb + C) * 2u; }
;     const size_t kstep = (size_t)(BK * 2);
;     const size_t hstepA = (size_t)HALF * g.lda * 2, hstepB = (size_t)HALF * g.ldb * 2;
;     const unsigned ldsw = (unsigned)wid * 1024u;
;     const int aoff = lds_byte(wr * 64 + fr, fq * 8), boff = lds_byte(wc * 32 + fr, fq * 8);
;     ...
;     Unit cur, nxt; int ui = 0;
;     if (!S.next(0, cur)) return;
;     f32x4 acc[2][2][4][2];
; #pragma unroll
;     for (int a = 0; a < 2; ++a)
; #pragma unroll
;         for (int b = 0; b < 2; ++b)
; #pragma unroll
;             for (int m = 0; m < 4; ++m)
; #pragma unroll
;                 for (int n = 0; n < 2; ++n) acc[a][b][m][n] = (f32x4){0.f, 0.f, 0.f, 0.f};
;     bf16x8 At[4][2], B0[2][2], B1[2][2];
;     const char* cA = (const char*)g.A + (size_t)cur.pm * 2 * hstepA; const char* cB = (const char*)g.Bt + ((size_t)(cur.pm / g.grp_tiles) * g.grp_brows + (size_t)cur.pn * BM) * g.ldb * 2;
;     S.a_ready(cur);
;     if constexpr (SP2) {
;         PG8_STAGE(PG8_SB(0, 0), cB, voffB); PG8_STAGE(PG8_SB(0, 1), cB + hstepB, voffB); PG8_STAGE(PG8_SA(0, 0), cA, voffA); PG8_STAGE(PG8_SA(0, 1), cA + hstepA, voffA);
;         if (wr == 1) PG8_BAR;
;         PG8_WAIT_V(2); PG8_BAR;
;         PG8_STAGE(PG8_SB(1, 0), cB + kstep, voffB); PG8_STAGE(PG8_SA(1, 0), cA + kstep, voffA); PG8_STAGE(PG8_SB(1, 1), cB + hstepB + kstep, voffB);
;         PG8_WAIT_V(6); PG8_BAR;
.LBB0_310:
	v_writelane_b32 v255, s29, 53
	v_mov_b32_e32 v0, v205
	v_readlane_b32 s0, v255, 0
	s_mov_b32 s1, s2
	v_mov_b32_e32 v1, v205
	s_waitcnt vmcnt(0) lgkmcnt(0)
	s_barrier
	s_and_b64 vcc, exec, s[4:5]
	v_add_u32_e32 v1, 0, v1
	v_add_u32_e32 v1, 0x200c8, v1
	ds_read_b64 v[2:3], v1
	v_mbcnt_lo_u32_b32 v0, -1, v0
	v_mbcnt_hi_u32_b32 v0, -1, v0
	v_lshl_add_u32 v1, s0, 6, v0
	s_waitcnt lgkmcnt(0)
	v_readfirstlane_b32 s7, v3
	v_readfirstlane_b32 s6, v2
	v_readfirstlane_b32 s0, v1
	s_cbranch_vccnz .LBB0_332
	v_lshlrev_b32_e32 v2, 4, v1
	v_add_u32_e32 v3, 0x2000, v2
	v_ashrrev_i32_e32 v4, 31, v3
	v_lshrrev_b32_e32 v4, 22, v4
	v_add_u32_e32 v4, v3, v4
	v_ashrrev_i32_e32 v4, 10, v4
	v_mul_i32_i24_e32 v5, 0x400, v4
	v_sub_u32_e32 v3, v3, v5
	v_lshrrev_b32_e32 v5, 4, v3
	v_bitop3_b32 v3, v5, v3, 32 bitop3:0x6c
	v_ashrrev_i32_e32 v5, 31, v3
	v_lshrrev_b32_e32 v5, 26, v5
	s_add_u32 s22, s6, 0x15a00000
	v_add_u32_e32 v5, v3, v5
	v_lshlrev_b32_e32 v7, 3, v4
	s_addc_u32 s23, s7, 0
	v_ashrrev_i32_e32 v6, 6, v5
	v_and_b32_e32 v7, -16, v7
	s_add_u32 s1, s6, s8
	v_add_u32_e32 v7, v6, v7
	s_addc_u32 s4, s7, s9
	v_and_b32_e32 v6, 3, v6
	s_mov_b32 s5, 0x1ffffe0
	v_lshrrev_b32_e32 v8, 2, v7
	v_lshlrev_b32_e32 v9, 1, v7
	v_and_b32_e32 v5, 0xc0, v5
	s_add_u32 s24, s1, 0xe00000
	v_and_or_b32 v6, v7, s5, v6
	v_and_b32_e32 v8, 4, v8
	v_and_b32_e32 v9, 24, v9
	v_lshlrev_b32_e32 v4, 5, v4
	v_sub_u32_e32 v3, v3, v5
	s_addc_u32 s25, s4, 0
	v_or3_b32 v6, v6, v8, v9
	s_movk_i32 s4, 0x180
	v_and_b32_e32 v4, 32, v4
	v_ashrrev_i16_sdwa v3, v254, sext(v3) dst_sel:DWORD dst_unused:UNUSED_PAD src0_sel:DWORD src1_sel:BYTE_0
	v_mul_lo_u32 v6, v6, s4
	v_add_u32_sdwa v3, v4, sext(v3) dst_sel:DWORD dst_unused:UNUSED_PAD src0_sel:DWORD src1_sel:WORD_0
	v_mul_lo_u32 v4, v7, s4
	v_add_lshl_u32 v128, v6, v3, 1
	v_add_lshl_u32 v130, v3, v4, 1
	v_bfe_i32 v3, v1, 27, 1
	v_lshrrev_b32_e32 v3, 22, v3
	v_add_u32_e32 v3, v2, v3
	v_and_b32_e32 v3, 0xfffffc00, v3
	v_sub_u32_e32 v2, v2, v3
	v_lshrrev_b32_e32 v3, 4, v2
	v_ashrrev_i32_e32 v5, 31, v1
	v_bitop3_b32 v2, v3, v2, 32 bitop3:0x6c
	v_lshrrev_b32_e32 v5, 26, v5
	v_ashrrev_i32_e32 v3, 31, v2
	v_add_u32_e32 v1, v1, v5
	v_lshrrev_b32_e32 v3, 26, v3
	v_ashrrev_i32_e32 v1, 6, v1
	v_add_u32_e32 v3, v2, v3
	v_lshlrev_b32_e32 v5, 3, v1
	v_ashrrev_i32_e32 v4, 6, v3
	v_and_b32_e32 v5, -16, v5
	v_add_u32_e32 v5, v4, v5
	v_and_b32_e32 v4, 3, v4
	v_lshrrev_b32_e32 v6, 2, v5
	v_lshlrev_b32_e32 v7, 1, v5
	v_and_b32_e32 v3, 0xc0, v3
	v_and_or_b32 v4, v5, s5, v4
	v_and_b32_e32 v6, 4, v6
	v_and_b32_e32 v7, 24, v7
	v_lshlrev_b32_e32 v1, 5, v1
	v_sub_u32_e32 v2, v2, v3
	s_ashr_i32 s1, s0, 6
	v_or3_b32 v4, v4, v6, v7
	v_and_b32_e32 v1, 32, v1
	v_ashrrev_i16_sdwa v2, v254, sext(v2) dst_sel:DWORD dst_unused:UNUSED_PAD src0_sel:DWORD src1_sel:BYTE_0
	s_ashr_i32 s26, s0, 8
	s_lshl_b32 s27, s1, 10
	v_mul_lo_u32 v4, v4, s4
	v_add_u32_sdwa v1, v1, sext(v2) dst_sel:DWORD dst_unused:UNUSED_PAD src0_sel:DWORD src1_sel:WORD_0
	v_mul_lo_u32 v2, v5, s4
	v_readlane_b32 s4, v255, 24
	s_add_u32 s20, s24, s4
	v_readlane_b32 s4, v255, 23
	s_addc_u32 s21, s25, s4
	s_add_i32 s28, s27, 0
	v_add_lshl_u32 v132, v4, v1, 1
	s_add_i32 m0, s28, 0x10000
	v_add_lshl_u32 v134, v1, v2, 1
	global_load_lds_dwordx4 v132, s[20:21] nt
	s_add_i32 m0, s28, 0x12000
	s_add_u32 s4, s20, 0x18000
	global_load_lds_dwordx4 v128, s[20:21] nt
	s_addc_u32 s5, s21, 0
	s_add_i32 m0, s28, 0x14000
	s_nop 0
	global_load_lds_dwordx4 v132, s[4:5] nt
	s_add_i32 m0, s28, 0x16000
	s_nop 0
	global_load_lds_dwordx4 v128, s[4:5] nt
	v_readlane_b32 s4, v255, 22
	s_add_u32 s18, s22, s4
	v_readlane_b32 s4, v255, 20
	s_addc_u32 s19, s23, s4
	s_add_i32 s29, s28, 0x2000
	s_mov_b32 m0, s28
	s_add_u32 s4, s18, 0x18000
	global_load_lds_dwordx4 v134, s[18:19] nt
	s_mov_b32 m0, s29
	s_addc_u32 s5, s19, 0
	s_add_i32 s30, s28, 0x4000
	global_load_lds_dwordx4 v130, s[18:19] nt
	s_mov_b32 m0, s30
	s_add_i32 s31, s28, 0x6000
	global_load_lds_dwordx4 v134, s[4:5] nt
	s_mov_b32 m0, s31
	s_cmp_eq_u32 s26, 1
	global_load_lds_dwordx4 v130, s[4:5] nt
	s_cselect_b64 s[8:9], -1, 0
	s_cmp_lg_u32 s26, 1
	s_cbranch_scc1 .LBB0_313
	s_barrier
.LBB0_313:
	v_and_b32_e32 v138, 15, v0
	v_bfe_u32 v139, v0, 4, 2
	v_lshlrev_b32_e32 v1, 6, v138
	v_lshlrev_b32_e32 v0, 2, v0
	v_mov_b32_e32 v133, v205
	s_and_b32 s34, s1, 3
	v_lshl_or_b32 v1, v139, 4, v1
	s_lshl_b32 s1, s26, 13
	v_and_b32_e32 v0, 32, v0
	v_lshl_add_u64 v[2:3], s[20:21], 0, v[132:133]
	v_mov_b32_e32 v129, v205
	v_bitop3_b32 v10, s1, v1, v0 bitop3:0xf6
	s_lshl_b32 s1, s34, 12
	v_lshl_add_u64 v[4:5], s[20:21], 0, v[128:129]
	v_mov_b32_e32 v135, v205
	v_bitop3_b32 v140, s1, v1, v0 bitop3:0xf6
	s_add_i32 m0, s28, 0x18000
	v_lshl_add_u64 v[0:1], v[2:3], 0, s[82:83]
	v_lshl_add_u64 v[6:7], s[18:19], 0, v[134:135]
	v_mov_b32_e32 v131, v205
	s_waitcnt vmcnt(2)
	s_barrier
	global_load_lds_dwordx4 v[0:1], off nt
	v_lshl_add_u64 v[0:1], v[4:5], 0, s[82:83]
	s_add_i32 m0, s28, 0x1a000
	s_add_i32 s35, s28, 0x8000
	s_add_i32 s36, s28, 0xa000
	v_lshl_add_u64 v[8:9], s[18:19], 0, v[130:131]
	global_load_lds_dwordx4 v[0:1], off nt
	v_lshl_add_u64 v[0:1], v[6:7], 0, s[82:83]
	s_mov_b32 m0, s35
	s_add_u32 s4, s20, 0x18080
	global_load_lds_dwordx4 v[0:1], off nt
	v_lshl_add_u64 v[0:1], v[8:9], 0, s[82:83]
	s_mov_b32 m0, s36
	s_addc_u32 s5, s21, 0
	global_load_lds_dwordx4 v[0:1], off nt
	s_add_i32 m0, s28, 0x1c000
	v_lshl_add_u64 v[0:1], s[4:5], 0, v[132:133]
	global_load_lds_dwordx4 v[0:1], off nt
	v_lshl_add_u64 v[0:1], s[4:5], 0, v[128:129]
	s_add_i32 m0, s28, 0x1e000
	s_cmpk_lt_u32 s0, 0x100
	global_load_lds_dwordx4 v[0:1], off nt
	s_waitcnt vmcnt(6)
	v_readlane_b32 s14, v255, 43
	v_add_u32_e32 v141, 0, v10
	s_cselect_b64 s[12:13], -1, 0
	v_readlane_b32 s15, v255, 44
	v_readlane_b32 s42, v255, 21
	s_barrier
	s_branch .LBB0_316

; #define PG8_STAGE(bufoff, gbase, voff) do { _Pragma("unroll") for (int _i = 0; _i < 2; ++_i) \
;         __builtin_amdgcn_global_load_lds((const unsigned*)((const char*)(gbase) + (voff)[_i]), (PG8_LAS unsigned*)(lds + (bufoff) + ldsw + _i * 8192), 16, 0, 0); } while (0)
; #define PG8_LDA(dst, b, h) do { _Pragma("unroll") for (int m = 0; m < 4; ++m) _Pragma("unroll") for (int k = 0; k < 2; ++k) dst[m][k] = *(const PG8_LAS bf16x8*)(lds + PG8_SA(b, h) + aoff + m * 2048 + k * 1024); } while (0)
; #define PG8_LDB(dst, b, h) do { _Pragma("unroll") for (int n = 0; n < 2; ++n) _Pragma("unroll") for (int k = 0; k < 2; ++k) dst[n][k] = *(const PG8_LAS bf16x8*)(lds + PG8_SB(b, h) + boff + n * 2048 + k * 1024); } while (0)
; #define PG8_MMA(ai, bj, At, Bt) do { __builtin_amdgcn_s_setprio(1); _Pragma("unroll") for (int m = 0; m < 4; ++m) _Pragma("unroll") for (int n = 0; n < 2; ++n) _Pragma("unroll") for (int k = 0; k < 2; ++k) \
;         acc[ai][bj][m][n] = __builtin_amdgcn_mfma_f32_16x16x32_bf16(Bt[n][k], At[m][k], acc[ai][bj][m][n], 0, 0, 0); __builtin_amdgcn_s_setprio(0); } while (0)
; #define PG8_WAIT_V(n) asm volatile("s_waitcnt vmcnt(" #n ")" ::: "memory")
; #define PG8_WAIT_L(n) asm volatile("s_waitcnt lgkmcnt(" #n ")" ::: "memory")
; #define PG8_BAR __builtin_amdgcn_s_barrier()
; #define PG8_SCHED __builtin_amdgcn_sched_barrier(0)
; template <class Epi, class Sched, bool ALIGN_EPI = false, bool SP2 = false>
; __device__ __forceinline__ void gemm_phase(PG8_LAS unsigned char* lds, const Gemm g, const Sched& S, const Epi& E, const int tid) {
;     ...
;             if constexpr (SP2) {
;             PG8_LDB(B0, 0, 0); PG8_LDB(B1, 0, 1); PG8_SCHED; PG8_LDA(At, 0, 0); PG8_STAGE(PG8_SA(1, 1), a1 + hstepA, voffA);
;             PG8_WAIT_V(8); PG8_WAIT_L(0); PG8_BAR; PG8_MMA(0, 0, At, B0); PG8_MMA(0, 1, At, B1); PG8_BAR; PG8_SCHED;
;             PG8_LDA(At, 0, 1); PG8_STAGE(PG8_SB(0, 0), b2, voffB); PG8_STAGE(PG8_SB(0, 1), b2 + hstepB, voffB); PG8_STAGE(PG8_SA(0, 0), a2, voffA);
;             PG8_WAIT_V(8); PG8_WAIT_L(0); PG8_BAR; PG8_MMA(1, 0, At, B0); PG8_MMA(1, 1, At, B1); PG8_BAR; PG8_SCHED;
.LBB0_326:
	s_add_i32 s47, 0, 0x10000
	s_add_i32 s49, 0, 0x14000
	v_add_u32_e32 v8, s47, v140
	v_add_u32_e32 v9, s49, v140
	ds_read_b128 v[10:13], v8
	ds_read_b128 v[14:17], v8 offset:1024
	ds_read_b128 v[18:21], v8 offset:2048
	ds_read_b128 v[22:25], v8 offset:3072
	ds_read_b128 v[26:29], v9
	ds_read_b128 v[30:33], v9 offset:1024
	ds_read_b128 v[34:37], v9 offset:2048
	ds_read_b128 v[38:41], v9 offset:3072
	s_add_u32 s54, s18, 0x18080
	s_addc_u32 s55, s19, 0
	s_add_i32 s57, s28, 0xc000
	v_lshl_add_u64 v[66:67], s[54:55], 0, v[134:135]
	s_mov_b32 m0, s57
	s_add_i32 s43, s28, 0xe000
	ds_read_b128 v[0:3], v141
	ds_read_b128 v[4:7], v141 offset:1024
	ds_read_b128 v[42:45], v141 offset:2048
	ds_read_b128 v[46:49], v141 offset:3072
	ds_read_b128 v[50:53], v141 offset:4096
	ds_read_b128 v[54:57], v141 offset:5120
	ds_read_b128 v[58:61], v141 offset:6144
	ds_read_b128 v[62:65], v141 offset:7168
	global_load_lds_dwordx4 v[66:67], off nt
	v_lshl_add_u64 v[66:67], s[54:55], 0, v[130:131]
	s_mov_b32 m0, s43
	s_nop 0
	global_load_lds_dwordx4 v[66:67], off nt
	s_waitcnt vmcnt(8)
	s_waitcnt lgkmcnt(0)
	s_barrier
	s_setprio 1
	s_waitcnt lgkmcnt(0)
	v_mfma_f32_16x16x32_bf16 v[66:69], v[10:13], v[0:3], 0
	v_mfma_f32_16x16x32_bf16 v[70:73], v[18:21], v[0:3], 0
	v_mfma_f32_16x16x32_bf16 v[74:77], v[10:13], v[42:45], 0
	v_mfma_f32_16x16x32_bf16 v[78:81], v[18:21], v[42:45], 0
	v_mfma_f32_16x16x32_bf16 v[82:85], v[10:13], v[50:53], 0
	v_mfma_f32_16x16x32_bf16 v[86:89], v[18:21], v[50:53], 0
	v_mfma_f32_16x16x32_bf16 v[90:93], v[10:13], v[58:61], 0
	v_mfma_f32_16x16x32_bf16 v[94:97], v[18:21], v[58:61], 0
	v_mfma_f32_16x16x32_bf16 v[66:69], v[14:17], v[4:7], v[66:69]
	v_mfma_f32_16x16x32_bf16 v[70:73], v[22:25], v[4:7], v[70:73]
	v_mfma_f32_16x16x32_bf16 v[74:77], v[14:17], v[46:49], v[74:77]
	v_mfma_f32_16x16x32_bf16 v[78:81], v[22:25], v[46:49], v[78:81]
	v_mfma_f32_16x16x32_bf16 v[82:85], v[14:17], v[54:57], v[82:85]
	v_mfma_f32_16x16x32_bf16 v[86:89], v[22:25], v[54:57], v[86:89]
	v_mfma_f32_16x16x32_bf16 v[90:93], v[14:17], v[62:65], v[90:93]
	v_mfma_f32_16x16x32_bf16 v[94:97], v[22:25], v[62:65], v[94:97]
	s_setprio 0
	s_setprio 1
	v_mfma_f32_16x16x32_bf16 v[98:101], v[26:29], v[0:3], 0
	v_mfma_f32_16x16x32_bf16 v[0:3], v[34:37], v[0:3], 0
	v_mfma_f32_16x16x32_bf16 v[102:105], v[38:41], v[4:7], v[0:3]
	v_mfma_f32_16x16x32_bf16 v[0:3], v[26:29], v[42:45], 0
	v_mfma_f32_16x16x32_bf16 v[106:109], v[30:33], v[46:49], v[0:3]
	v_mfma_f32_16x16x32_bf16 v[0:3], v[34:37], v[42:45], 0
	v_mfma_f32_16x16x32_bf16 v[42:45], v[38:41], v[46:49], v[0:3]
	v_mfma_f32_16x16x32_bf16 v[0:3], v[26:29], v[50:53], 0
	v_mfma_f32_16x16x32_bf16 v[46:49], v[30:33], v[54:57], v[0:3]
	v_mfma_f32_16x16x32_bf16 v[0:3], v[34:37], v[50:53], 0
	v_mfma_f32_16x16x32_bf16 v[50:53], v[38:41], v[54:57], v[0:3]
	v_mfma_f32_16x16x32_bf16 v[0:3], v[26:29], v[58:61], 0
	v_mfma_f32_16x16x32_bf16 v[54:57], v[30:33], v[62:65], v[0:3]
	v_mfma_f32_16x16x32_bf16 v[0:3], v[34:37], v[58:61], 0
	v_mfma_f32_16x16x32_bf16 v[98:101], v[30:33], v[4:7], v[98:101]
	v_mfma_f32_16x16x32_bf16 v[58:61], v[38:41], v[62:65], v[0:3]
	s_setprio 0
	s_barrier
	s_nop 3
	v_lshl_add_u64 v[0:1], s[20:21], 0, v[132:133]
	s_add_i32 s54, s47, s27
	v_lshl_add_u64 v[2:3], v[0:1], 0, s[84:85]
	s_mov_b32 m0, s54
	s_add_i32 s47, s54, 0x2000
	ds_read_b128 v[62:65], v141 offset:16384
	ds_read_b128 v[110:113], v141 offset:17408
	ds_read_b128 v[114:117], v141 offset:18432
	ds_read_b128 v[118:121], v141 offset:19456
	ds_read_b128 v[122:125], v141 offset:20480
	ds_read_b128 v[142:145], v141 offset:21504
	ds_read_b128 v[146:149], v141 offset:22528
	ds_read_b128 v[150:153], v141 offset:23552
	global_load_lds_dwordx4 v[2:3], off nt
	v_lshl_add_u64 v[2:3], s[20:21], 0, v[128:129]
	s_add_u32 s58, s20, 0x18100
	v_lshl_add_u64 v[4:5], v[2:3], 0, s[84:85]
	s_mov_b32 m0, s47
	s_addc_u32 s59, s21, 0
	s_add_i32 s49, s49, s27
	global_load_lds_dwordx4 v[4:5], off nt
	v_lshl_add_u64 v[4:5], s[58:59], 0, v[132:133]
	s_mov_b32 m0, s49
	s_add_i32 s50, s49, 0x2000
	global_load_lds_dwordx4 v[4:5], off nt
	v_lshl_add_u64 v[4:5], s[58:59], 0, v[128:129]
	s_mov_b32 m0, s50
	s_nop 0
	global_load_lds_dwordx4 v[4:5], off nt
	v_lshl_add_u64 v[4:5], s[18:19], 0, v[134:135]
	v_lshl_add_u64 v[6:7], v[4:5], 0, s[84:85]
	s_mov_b32 m0, s28
	s_nop 0
	global_load_lds_dwordx4 v[6:7], off nt
	v_lshl_add_u64 v[6:7], s[18:19], 0, v[130:131]
	v_lshl_add_u64 v[126:127], v[6:7], 0, s[84:85]
	s_mov_b32 m0, s29
	s_nop 0
	global_load_lds_dwordx4 v[126:127], off nt
	s_waitcnt vmcnt(8)
	s_waitcnt lgkmcnt(0)
	s_barrier
; #define PG8_STAGE(bufoff, gbase, voff) do { _Pragma("unroll") for (int _i = 0; _i < 2; ++_i) \
;         __builtin_amdgcn_global_load_lds((const unsigned*)((const char*)(gbase) + (voff)[_i]), (PG8_LAS unsigned*)(lds + (bufoff) + ldsw + _i * 8192), 16, 0, 0); } while (0)
; #define PG8_LDA(dst, b, h) do { _Pragma("unroll") for (int m = 0; m < 4; ++m) _Pragma("unroll") for (int k = 0; k < 2; ++k) dst[m][k] = *(const PG8_LAS bf16x8*)(lds + PG8_SA(b, h) + aoff + m * 2048 + k * 1024); } while (0)
; #define PG8_LDB(dst, b, h) do { _Pragma("unroll") for (int n = 0; n < 2; ++n) _Pragma("unroll") for (int k = 0; k < 2; ++k) dst[n][k] = *(const PG8_LAS bf16x8*)(lds + PG8_SB(b, h) + boff + n * 2048 + k * 1024); } while (0)
; #define PG8_MMA(ai, bj, At, Bt) do { __builtin_amdgcn_s_setprio(1); _Pragma("unroll") for (int m = 0; m < 4; ++m) _Pragma("unroll") for (int n = 0; n < 2; ++n) _Pragma("unroll") for (int k = 0; k < 2; ++k) \
;         acc[ai][bj][m][n] = __builtin_amdgcn_mfma_f32_16x16x32_bf16(Bt[n][k], At[m][k], acc[ai][bj][m][n], 0, 0, 0); __builtin_amdgcn_s_setprio(0); } while (0)
; #define PG8_WAIT_V(n) asm volatile("s_waitcnt vmcnt(" #n ")" ::: "memory")
; #define PG8_WAIT_L(n) asm volatile("s_waitcnt lgkmcnt(" #n ")" ::: "memory")
; #define PG8_BAR __builtin_amdgcn_s_barrier()
; #define PG8_SCHED __builtin_amdgcn_sched_barrier(0)
; template <class Epi, class Sched, bool ALIGN_EPI = false, bool SP2 = false>
; __device__ __forceinline__ void gemm_phase(PG8_LAS unsigned char* lds, const Gemm g, const Sched& S, const Epi& E, const int tid) {
;     ...
;             PG8_WAIT_V(8); PG8_WAIT_L(0); PG8_BAR; PG8_MMA(1, 0, At, B0); PG8_MMA(1, 1, At, B1); PG8_BAR; PG8_SCHED;
;             PG8_LDB(B0, 1, 0); PG8_LDB(B1, 1, 1); PG8_SCHED; PG8_LDA(At, 1, 0); PG8_STAGE(PG8_SA(0, 1), a2 + hstepA, voffA);
;             PG8_WAIT_V(8); PG8_WAIT_L(0); PG8_BAR; PG8_MMA(0, 0, At, B0); PG8_MMA(0, 1, At, B1); PG8_BAR; PG8_SCHED;
	s_setprio 1
	s_waitcnt lgkmcnt(0)
	v_mfma_f32_16x16x32_bf16 v[154:157], v[10:13], v[62:65], 0
	v_mfma_f32_16x16x32_bf16 v[162:165], v[10:13], v[114:117], 0
	v_mfma_f32_16x16x32_bf16 v[170:173], v[10:13], v[122:125], 0
	v_mfma_f32_16x16x32_bf16 v[10:13], v[10:13], v[146:149], 0
	v_mfma_f32_16x16x32_bf16 v[154:157], v[14:17], v[110:113], v[154:157]
	v_mfma_f32_16x16x32_bf16 v[158:161], v[18:21], v[62:65], 0
	v_mfma_f32_16x16x32_bf16 v[162:165], v[14:17], v[118:121], v[162:165]
	v_mfma_f32_16x16x32_bf16 v[166:169], v[18:21], v[114:117], 0
	v_mfma_f32_16x16x32_bf16 v[170:173], v[14:17], v[142:145], v[170:173]
	v_mfma_f32_16x16x32_bf16 v[174:177], v[18:21], v[122:125], 0
	v_mfma_f32_16x16x32_bf16 v[12:15], v[14:17], v[150:153], v[10:13]
	v_mfma_f32_16x16x32_bf16 v[16:19], v[18:21], v[146:149], 0
	v_mfma_f32_16x16x32_bf16 v[16:19], v[22:25], v[150:153], v[16:19]
	v_mfma_f32_16x16x32_bf16 v[158:161], v[22:25], v[110:113], v[158:161]
	v_mfma_f32_16x16x32_bf16 v[166:169], v[22:25], v[118:121], v[166:169]
	v_mfma_f32_16x16x32_bf16 v[174:177], v[22:25], v[142:145], v[174:177]
	s_setprio 0
	s_setprio 1
	v_mfma_f32_16x16x32_bf16 v[20:23], v[26:29], v[62:65], 0
	v_mfma_f32_16x16x32_bf16 v[62:65], v[34:37], v[62:65], 0
	v_mfma_f32_16x16x32_bf16 v[20:23], v[30:33], v[110:113], v[20:23]
	v_mfma_f32_16x16x32_bf16 v[62:65], v[38:41], v[110:113], v[62:65]
	v_mfma_f32_16x16x32_bf16 v[110:113], v[26:29], v[114:117], 0
	v_mfma_f32_16x16x32_bf16 v[114:117], v[34:37], v[114:117], 0
	v_mfma_f32_16x16x32_bf16 v[110:113], v[30:33], v[118:121], v[110:113]
	v_mfma_f32_16x16x32_bf16 v[114:117], v[38:41], v[118:121], v[114:117]
	v_mfma_f32_16x16x32_bf16 v[118:121], v[26:29], v[122:125], 0
	v_mfma_f32_16x16x32_bf16 v[24:27], v[26:29], v[146:149], 0
	v_mfma_f32_16x16x32_bf16 v[118:121], v[30:33], v[142:145], v[118:121]
	v_mfma_f32_16x16x32_bf16 v[122:125], v[34:37], v[122:125], 0
	v_mfma_f32_16x16x32_bf16 v[24:27], v[30:33], v[150:153], v[24:27]
	v_mfma_f32_16x16x32_bf16 v[28:31], v[34:37], v[146:149], 0
	v_mfma_f32_16x16x32_bf16 v[122:125], v[38:41], v[142:145], v[122:125]
	v_mfma_f32_16x16x32_bf16 v[28:31], v[38:41], v[150:153], v[28:31]
	s_setprio 0
	s_barrier
	s_add_i32 s55, 0, 0x18000
	s_add_i32 s56, 0, 0x1c000
	v_add_u32_e32 v10, s55, v140
	v_add_u32_e32 v11, s56, v140
	ds_read_b128 v[32:35], v10
	ds_read_b128 v[36:39], v10 offset:1024
	ds_read_b128 v[142:145], v10 offset:2048
	ds_read_b128 v[146:149], v10 offset:3072
	ds_read_b128 v[150:153], v11
	ds_read_b128 v[178:181], v11 offset:1024
	ds_read_b128 v[182:185], v11 offset:2048
	ds_read_b128 v[186:189], v11 offset:3072
	s_add_u32 s58, s18, 0x18100
	s_addc_u32 s59, s19, 0
	s_mov_b32 m0, s30
	v_lshl_add_u64 v[40:41], s[58:59], 0, v[134:135]
	ds_read_b128 v[190:193], v141 offset:32768
	ds_read_b128 v[194:197], v141 offset:33792
	ds_read_b128 v[198:201], v141 offset:34816
	ds_read_b128 v[218:221], v141 offset:35840
	ds_read_b128 v[222:225], v141 offset:36864
	ds_read_b128 v[226:229], v141 offset:37888
	ds_read_b128 v[238:241], v141 offset:38912
	ds_read_b128 v[242:245], v141 offset:39936
	global_load_lds_dwordx4 v[40:41], off nt
	v_lshl_add_u64 v[40:41], s[58:59], 0, v[130:131]
	s_mov_b32 m0, s31
	s_nop 0
	global_load_lds_dwordx4 v[40:41], off nt
	s_waitcnt vmcnt(8)
	s_waitcnt lgkmcnt(0)
	s_barrier
	s_setprio 1
	s_waitcnt lgkmcnt(0)
	v_mfma_f32_16x16x32_bf16 v[66:69], v[32:35], v[190:193], v[66:69]
	v_mfma_f32_16x16x32_bf16 v[70:73], v[142:145], v[190:193], v[70:73]
	v_mfma_f32_16x16x32_bf16 v[74:77], v[32:35], v[198:201], v[74:77]
	v_mfma_f32_16x16x32_bf16 v[78:81], v[142:145], v[198:201], v[78:81]
	v_mfma_f32_16x16x32_bf16 v[82:85], v[32:35], v[222:225], v[82:85]
	v_mfma_f32_16x16x32_bf16 v[86:89], v[142:145], v[222:225], v[86:89]
	v_mfma_f32_16x16x32_bf16 v[90:93], v[32:35], v[238:241], v[90:93]
	v_mfma_f32_16x16x32_bf16 v[94:97], v[142:145], v[238:241], v[94:97]
	v_mfma_f32_16x16x32_bf16 v[66:69], v[36:39], v[194:197], v[66:69]
	v_mfma_f32_16x16x32_bf16 v[70:73], v[146:149], v[194:197], v[70:73]
	v_mfma_f32_16x16x32_bf16 v[74:77], v[36:39], v[218:221], v[74:77]
	v_mfma_f32_16x16x32_bf16 v[78:81], v[146:149], v[218:221], v[78:81]
	v_mfma_f32_16x16x32_bf16 v[82:85], v[36:39], v[226:229], v[82:85]
	v_mfma_f32_16x16x32_bf16 v[86:89], v[146:149], v[226:229], v[86:89]
	v_mfma_f32_16x16x32_bf16 v[90:93], v[36:39], v[242:245], v[90:93]
	v_mfma_f32_16x16x32_bf16 v[94:97], v[146:149], v[242:245], v[94:97]
	s_setprio 0
	s_setprio 1
	v_mfma_f32_16x16x32_bf16 v[98:101], v[150:153], v[190:193], v[98:101]
	v_mfma_f32_16x16x32_bf16 v[102:105], v[182:185], v[190:193], v[102:105]
	v_mfma_f32_16x16x32_bf16 v[106:109], v[150:153], v[198:201], v[106:109]
	v_mfma_f32_16x16x32_bf16 v[40:43], v[182:185], v[198:201], v[42:45]
	v_mfma_f32_16x16x32_bf16 v[44:47], v[150:153], v[222:225], v[46:49]
	v_mfma_f32_16x16x32_bf16 v[48:51], v[182:185], v[222:225], v[50:53]
	v_mfma_f32_16x16x32_bf16 v[52:55], v[150:153], v[238:241], v[54:57]
	v_mfma_f32_16x16x32_bf16 v[56:59], v[182:185], v[238:241], v[58:61]
	v_mfma_f32_16x16x32_bf16 v[98:101], v[178:181], v[194:197], v[98:101]
	v_mfma_f32_16x16x32_bf16 v[102:105], v[186:189], v[194:197], v[102:105]
	v_mfma_f32_16x16x32_bf16 v[106:109], v[178:181], v[218:221], v[106:109]
	v_mfma_f32_16x16x32_bf16 v[40:43], v[186:189], v[218:221], v[40:43]
	v_mfma_f32_16x16x32_bf16 v[44:47], v[178:181], v[226:229], v[44:47]
	v_mfma_f32_16x16x32_bf16 v[48:51], v[186:189], v[226:229], v[48:51]
	v_mfma_f32_16x16x32_bf16 v[52:55], v[178:181], v[242:245], v[52:55]
	v_mfma_f32_16x16x32_bf16 v[56:59], v[186:189], v[242:245], v[56:59]
	s_setprio 0
	s_barrier
; #define PG8_STAGE(bufoff, gbase, voff) do { _Pragma("unroll") for (int _i = 0; _i < 2; ++_i) \
;         __builtin_amdgcn_global_load_lds((const unsigned*)((const char*)(gbase) + (voff)[_i]), (PG8_LAS unsigned*)(lds + (bufoff) + ldsw + _i * 8192), 16, 0, 0); } while (0)
; #define PG8_LDA(dst, b, h) do { _Pragma("unroll") for (int m = 0; m < 4; ++m) _Pragma("unroll") for (int k = 0; k < 2; ++k) dst[m][k] = *(const PG8_LAS bf16x8*)(lds + PG8_SA(b, h) + aoff + m * 2048 + k * 1024); } while (0)
; #define PG8_MMA(ai, bj, At, Bt) do { __builtin_amdgcn_s_setprio(1); _Pragma("unroll") for (int m = 0; m < 4; ++m) _Pragma("unroll") for (int n = 0; n < 2; ++n) _Pragma("unroll") for (int k = 0; k < 2; ++k) \
;         acc[ai][bj][m][n] = __builtin_amdgcn_mfma_f32_16x16x32_bf16(Bt[n][k], At[m][k], acc[ai][bj][m][n], 0, 0, 0); __builtin_amdgcn_s_setprio(0); } while (0)
; #define PG8_WAIT_V(n) asm volatile("s_waitcnt vmcnt(" #n ")" ::: "memory")
; #define PG8_WAIT_L(n) asm volatile("s_waitcnt lgkmcnt(" #n ")" ::: "memory")
; #define PG8_BAR __builtin_amdgcn_s_barrier()
; #define PG8_SCHED __builtin_amdgcn_sched_barrier(0)
; template <class Epi, class Sched, bool ALIGN_EPI = false, bool SP2 = false>
; __device__ __forceinline__ void gemm_phase(PG8_LAS unsigned char* lds, const Gemm g, const Sched& S, const Epi& E, const int tid) {
;     ...
;             PG8_WAIT_V(8); PG8_WAIT_L(0); PG8_BAR; PG8_MMA(0, 0, At, B0); PG8_MMA(0, 1, At, B1); PG8_BAR; PG8_SCHED;
;             PG8_LDA(At, 1, 1); PG8_STAGE(PG8_SB(1, 0), b3, voffB); PG8_STAGE(PG8_SB(1, 1), b3 + hstepB, voffB); PG8_STAGE(PG8_SA(1, 0), a3, voffA);
;             PG8_WAIT_V(8); PG8_WAIT_L(0); PG8_BAR; PG8_MMA(1, 0, At, B0); PG8_MMA(1, 1, At, B1); PG8_BAR; PG8_SCHED;
	s_add_i32 s59, s55, s27
	s_add_i32 s55, s59, 0x2000
	v_lshl_add_u64 v[60:61], v[0:1], 0, s[94:95]
	s_mov_b32 m0, s59
	s_add_u32 s60, s20, 0x18180
	ds_read_b128 v[190:193], v141 offset:49152
	ds_read_b128 v[194:197], v141 offset:50176
	ds_read_b128 v[198:201], v141 offset:51200
	ds_read_b128 v[218:221], v141 offset:52224
	ds_read_b128 v[222:225], v141 offset:53248
	ds_read_b128 v[226:229], v141 offset:54272
	ds_read_b128 v[238:241], v141 offset:55296
	ds_read_b128 v[242:245], v141 offset:56320
	global_load_lds_dwordx4 v[60:61], off nt
	v_lshl_add_u64 v[60:61], v[2:3], 0, s[94:95]
	s_mov_b32 m0, s55
	s_addc_u32 s61, s21, 0
	s_add_i32 s56, s56, s27
	global_load_lds_dwordx4 v[60:61], off nt
	v_lshl_add_u64 v[60:61], s[60:61], 0, v[132:133]
	s_mov_b32 m0, s56
	s_add_i32 s58, s56, 0x2000
	global_load_lds_dwordx4 v[60:61], off nt
	v_lshl_add_u64 v[60:61], s[60:61], 0, v[128:129]
	s_mov_b32 m0, s58
	s_nop 0
	global_load_lds_dwordx4 v[60:61], off nt
	v_lshl_add_u64 v[60:61], v[4:5], 0, s[94:95]
	s_mov_b32 m0, s35
	s_nop 0
	global_load_lds_dwordx4 v[60:61], off nt
	v_lshl_add_u64 v[60:61], v[6:7], 0, s[94:95]
	s_mov_b32 m0, s36
	s_nop 0
	global_load_lds_dwordx4 v[60:61], off nt
	s_waitcnt vmcnt(8)
	s_waitcnt lgkmcnt(0)
	s_barrier
	s_setprio 1
	s_waitcnt lgkmcnt(0)
	v_mfma_f32_16x16x32_bf16 v[12:15], v[32:35], v[238:241], v[12:15]
	v_mfma_f32_16x16x32_bf16 v[16:19], v[142:145], v[238:241], v[16:19]
	v_mfma_f32_16x16x32_bf16 v[154:157], v[32:35], v[190:193], v[154:157]
	v_mfma_f32_16x16x32_bf16 v[158:161], v[142:145], v[190:193], v[158:161]
	v_mfma_f32_16x16x32_bf16 v[162:165], v[32:35], v[198:201], v[162:165]
	v_mfma_f32_16x16x32_bf16 v[166:169], v[142:145], v[198:201], v[166:169]
	v_mfma_f32_16x16x32_bf16 v[170:173], v[32:35], v[222:225], v[170:173]
	v_mfma_f32_16x16x32_bf16 v[174:177], v[142:145], v[222:225], v[174:177]
	v_mfma_f32_16x16x32_bf16 v[12:15], v[36:39], v[242:245], v[12:15]
	v_mfma_f32_16x16x32_bf16 v[16:19], v[146:149], v[242:245], v[16:19]
	v_mfma_f32_16x16x32_bf16 v[154:157], v[36:39], v[194:197], v[154:157]
	v_mfma_f32_16x16x32_bf16 v[158:161], v[146:149], v[194:197], v[158:161]
	v_mfma_f32_16x16x32_bf16 v[162:165], v[36:39], v[218:221], v[162:165]
	v_mfma_f32_16x16x32_bf16 v[166:169], v[146:149], v[218:221], v[166:169]
	v_mfma_f32_16x16x32_bf16 v[170:173], v[36:39], v[226:229], v[170:173]
	v_mfma_f32_16x16x32_bf16 v[174:177], v[146:149], v[226:229], v[174:177]
	s_setprio 0
	s_setprio 1
	v_mfma_f32_16x16x32_bf16 v[20:23], v[150:153], v[190:193], v[20:23]
	v_mfma_f32_16x16x32_bf16 v[32:35], v[182:185], v[190:193], v[62:65]
	v_mfma_f32_16x16x32_bf16 v[36:39], v[150:153], v[198:201], v[110:113]
	v_mfma_f32_16x16x32_bf16 v[60:63], v[182:185], v[198:201], v[114:117]
	v_mfma_f32_16x16x32_bf16 v[110:113], v[150:153], v[222:225], v[118:121]
	v_mfma_f32_16x16x32_bf16 v[114:117], v[182:185], v[222:225], v[122:125]
	v_mfma_f32_16x16x32_bf16 v[24:27], v[150:153], v[238:241], v[24:27]
	v_mfma_f32_16x16x32_bf16 v[28:31], v[182:185], v[238:241], v[28:31]
	v_mfma_f32_16x16x32_bf16 v[20:23], v[178:181], v[194:197], v[20:23]
	v_mfma_f32_16x16x32_bf16 v[32:35], v[186:189], v[194:197], v[32:35]
	v_mfma_f32_16x16x32_bf16 v[36:39], v[178:181], v[218:221], v[36:39]
	v_mfma_f32_16x16x32_bf16 v[60:63], v[186:189], v[218:221], v[60:63]
	v_mfma_f32_16x16x32_bf16 v[110:113], v[178:181], v[226:229], v[110:113]
	v_mfma_f32_16x16x32_bf16 v[114:117], v[186:189], v[226:229], v[114:117]
	v_mfma_f32_16x16x32_bf16 v[24:27], v[178:181], v[242:245], v[24:27]
	v_mfma_f32_16x16x32_bf16 v[28:31], v[186:189], v[242:245], v[28:31]
	s_setprio 0
	s_barrier
	ds_read_b128 v[118:121], v8
	ds_read_b128 v[122:125], v8 offset:1024
	ds_read_b128 v[142:145], v8 offset:2048
	ds_read_b128 v[146:149], v8 offset:3072
	ds_read_b128 v[150:153], v9
	ds_read_b128 v[178:181], v9 offset:1024
	ds_read_b128 v[182:185], v9 offset:2048
	ds_read_b128 v[186:189], v9 offset:3072
	s_add_u32 s60, s18, 0x18180
	s_addc_u32 s61, s19, 0
	s_mov_b32 m0, s57
	v_lshl_add_u64 v[64:65], s[60:61], 0, v[134:135]
	ds_read_b128 v[190:193], v141
	ds_read_b128 v[194:197], v141 offset:1024
	ds_read_b128 v[198:201], v141 offset:2048
	ds_read_b128 v[218:221], v141 offset:3072
	ds_read_b128 v[222:225], v141 offset:4096
	ds_read_b128 v[226:229], v141 offset:5120
	ds_read_b128 v[238:241], v141 offset:6144
	ds_read_b128 v[242:245], v141 offset:7168
	global_load_lds_dwordx4 v[64:65], off nt
	v_lshl_add_u64 v[64:65], s[60:61], 0, v[130:131]
	s_mov_b32 m0, s43
	s_nop 0
	global_load_lds_dwordx4 v[64:65], off nt
	s_waitcnt vmcnt(8)
	s_waitcnt lgkmcnt(0)
	s_barrier
; #define PG8_STAGE(bufoff, gbase, voff) do { _Pragma("unroll") for (int _i = 0; _i < 2; ++_i) \
;         __builtin_amdgcn_global_load_lds((const unsigned*)((const char*)(gbase) + (voff)[_i]), (PG8_LAS unsigned*)(lds + (bufoff) + ldsw + _i * 8192), 16, 0, 0); } while (0)
; #define PG8_LDA(dst, b, h) do { _Pragma("unroll") for (int m = 0; m < 4; ++m) _Pragma("unroll") for (int k = 0; k < 2; ++k) dst[m][k] = *(const PG8_LAS bf16x8*)(lds + PG8_SA(b, h) + aoff + m * 2048 + k * 1024); } while (0)
; #define PG8_LDB(dst, b, h) do { _Pragma("unroll") for (int n = 0; n < 2; ++n) _Pragma("unroll") for (int k = 0; k < 2; ++k) dst[n][k] = *(const PG8_LAS bf16x8*)(lds + PG8_SB(b, h) + boff + n * 2048 + k * 1024); } while (0)
; #define PG8_MMA(ai, bj, At, Bt) do { __builtin_amdgcn_s_setprio(1); _Pragma("unroll") for (int m = 0; m < 4; ++m) _Pragma("unroll") for (int n = 0; n < 2; ++n) _Pragma("unroll") for (int k = 0; k < 2; ++k) \
;         acc[ai][bj][m][n] = __builtin_amdgcn_mfma_f32_16x16x32_bf16(Bt[n][k], At[m][k], acc[ai][bj][m][n], 0, 0, 0); __builtin_amdgcn_s_setprio(0); } while (0)
; #define PG8_WAIT_V(n) asm volatile("s_waitcnt vmcnt(" #n ")" ::: "memory")
; #define PG8_WAIT_L(n) asm volatile("s_waitcnt lgkmcnt(" #n ")" ::: "memory")
; #define PG8_BAR __builtin_amdgcn_s_barrier()
; #define PG8_SCHED __builtin_amdgcn_sched_barrier(0)
; template <class Epi, class Sched, bool ALIGN_EPI = false, bool SP2 = false>
; __device__ __forceinline__ void gemm_phase(PG8_LAS unsigned char* lds, const Gemm g, const Sched& S, const Epi& E, const int tid) {
;     ...
;             PG8_LDB(B0, 0, 0); PG8_LDB(B1, 0, 1); PG8_SCHED; PG8_LDA(At, 0, 0); PG8_STAGE(PG8_SA(1, 1), a1 + hstepA, voffA);
;             PG8_WAIT_V(8); PG8_WAIT_L(0); PG8_BAR; PG8_MMA(0, 0, At, B0); PG8_MMA(0, 1, At, B1); PG8_BAR; PG8_SCHED;
;             PG8_LDA(At, 0, 1); PG8_STAGE(PG8_SB(0, 0), b2, voffB); PG8_STAGE(PG8_SB(0, 1), b2 + hstepB, voffB); PG8_STAGE(PG8_SA(0, 0), a2, voffA);
;             PG8_WAIT_V(8); PG8_WAIT_L(0); PG8_BAR; PG8_MMA(1, 0, At, B0); PG8_MMA(1, 1, At, B1); PG8_BAR; PG8_SCHED;
;             PG8_LDB(B0, 1, 0); PG8_LDB(B1, 1, 1); PG8_SCHED; PG8_LDA(At, 1, 0); PG8_STAGE(PG8_SA(0, 1), a2 + hstepA, voffA);
	s_setprio 1
	s_waitcnt lgkmcnt(0)
	v_mfma_f32_16x16x32_bf16 v[64:67], v[118:121], v[190:193], v[66:69]
	v_mfma_f32_16x16x32_bf16 v[68:71], v[142:145], v[190:193], v[70:73]
	v_mfma_f32_16x16x32_bf16 v[72:75], v[118:121], v[198:201], v[74:77]
	v_mfma_f32_16x16x32_bf16 v[76:79], v[142:145], v[198:201], v[78:81]
	v_mfma_f32_16x16x32_bf16 v[80:83], v[118:121], v[222:225], v[82:85]
	v_mfma_f32_16x16x32_bf16 v[84:87], v[142:145], v[222:225], v[86:89]
	v_mfma_f32_16x16x32_bf16 v[88:91], v[118:121], v[238:241], v[90:93]
	v_mfma_f32_16x16x32_bf16 v[92:95], v[142:145], v[238:241], v[94:97]
	v_mfma_f32_16x16x32_bf16 v[64:67], v[122:125], v[194:197], v[64:67]
	v_mfma_f32_16x16x32_bf16 v[68:71], v[146:149], v[194:197], v[68:71]
	v_mfma_f32_16x16x32_bf16 v[72:75], v[122:125], v[218:221], v[72:75]
	v_mfma_f32_16x16x32_bf16 v[76:79], v[146:149], v[218:221], v[76:79]
	v_mfma_f32_16x16x32_bf16 v[80:83], v[122:125], v[226:229], v[80:83]
	v_mfma_f32_16x16x32_bf16 v[84:87], v[146:149], v[226:229], v[84:87]
	v_mfma_f32_16x16x32_bf16 v[88:91], v[122:125], v[242:245], v[88:91]
	v_mfma_f32_16x16x32_bf16 v[92:95], v[146:149], v[242:245], v[92:95]
	s_setprio 0
	s_setprio 1
	v_mfma_f32_16x16x32_bf16 v[96:99], v[150:153], v[190:193], v[98:101]
	v_mfma_f32_16x16x32_bf16 v[100:103], v[182:185], v[190:193], v[102:105]
	v_mfma_f32_16x16x32_bf16 v[104:107], v[150:153], v[198:201], v[106:109]
	v_mfma_f32_16x16x32_bf16 v[40:43], v[182:185], v[198:201], v[40:43]
	v_mfma_f32_16x16x32_bf16 v[44:47], v[150:153], v[222:225], v[44:47]
	v_mfma_f32_16x16x32_bf16 v[48:51], v[182:185], v[222:225], v[48:51]
	v_mfma_f32_16x16x32_bf16 v[52:55], v[150:153], v[238:241], v[52:55]
	v_mfma_f32_16x16x32_bf16 v[56:59], v[182:185], v[238:241], v[56:59]
	v_mfma_f32_16x16x32_bf16 v[96:99], v[178:181], v[194:197], v[96:99]
	v_mfma_f32_16x16x32_bf16 v[100:103], v[186:189], v[194:197], v[100:103]
	v_mfma_f32_16x16x32_bf16 v[104:107], v[178:181], v[218:221], v[104:107]
	v_mfma_f32_16x16x32_bf16 v[40:43], v[186:189], v[218:221], v[40:43]
	v_mfma_f32_16x16x32_bf16 v[44:47], v[178:181], v[226:229], v[44:47]
	v_mfma_f32_16x16x32_bf16 v[48:51], v[186:189], v[226:229], v[48:51]
	v_mfma_f32_16x16x32_bf16 v[52:55], v[178:181], v[242:245], v[52:55]
	v_mfma_f32_16x16x32_bf16 v[56:59], v[186:189], v[242:245], v[56:59]
	s_setprio 0
	s_barrier
	s_mov_b32 m0, s54
	v_lshl_add_u64 v[108:109], v[0:1], 0, s[92:93]
	s_add_u32 s60, s20, 0x18200
	ds_read_b128 v[190:193], v141 offset:16384
	ds_read_b128 v[194:197], v141 offset:17408
	ds_read_b128 v[198:201], v141 offset:18432
	ds_read_b128 v[218:221], v141 offset:19456
	ds_read_b128 v[222:225], v141 offset:20480
	ds_read_b128 v[226:229], v141 offset:21504
	ds_read_b128 v[238:241], v141 offset:22528
	ds_read_b128 v[242:245], v141 offset:23552
	global_load_lds_dwordx4 v[108:109], off nt
	v_lshl_add_u64 v[108:109], v[2:3], 0, s[92:93]
	s_mov_b32 m0, s47
	s_addc_u32 s61, s21, 0
	global_load_lds_dwordx4 v[108:109], off nt
	v_lshl_add_u64 v[108:109], s[60:61], 0, v[132:133]
	s_mov_b32 m0, s49
	s_nop 0
	global_load_lds_dwordx4 v[108:109], off nt
	v_lshl_add_u64 v[108:109], s[60:61], 0, v[128:129]
	s_mov_b32 m0, s50
	s_nop 0
	global_load_lds_dwordx4 v[108:109], off nt
	v_lshl_add_u64 v[108:109], v[4:5], 0, s[92:93]
	s_mov_b32 m0, s28
	s_nop 0
	global_load_lds_dwordx4 v[108:109], off nt
	v_lshl_add_u64 v[108:109], v[6:7], 0, s[92:93]
	s_mov_b32 m0, s29
	s_nop 0
	global_load_lds_dwordx4 v[108:109], off nt
	s_waitcnt vmcnt(8)
	s_waitcnt lgkmcnt(0)
	s_barrier
	s_setprio 1
	s_waitcnt lgkmcnt(0)
	v_mfma_f32_16x16x32_bf16 v[12:15], v[118:121], v[238:241], v[12:15]
	v_mfma_f32_16x16x32_bf16 v[16:19], v[142:145], v[238:241], v[16:19]
	v_mfma_f32_16x16x32_bf16 v[154:157], v[118:121], v[190:193], v[154:157]
	v_mfma_f32_16x16x32_bf16 v[158:161], v[142:145], v[190:193], v[158:161]
	v_mfma_f32_16x16x32_bf16 v[162:165], v[118:121], v[198:201], v[162:165]
	v_mfma_f32_16x16x32_bf16 v[166:169], v[142:145], v[198:201], v[166:169]
	v_mfma_f32_16x16x32_bf16 v[170:173], v[118:121], v[222:225], v[170:173]
	v_mfma_f32_16x16x32_bf16 v[174:177], v[142:145], v[222:225], v[174:177]
	v_mfma_f32_16x16x32_bf16 v[12:15], v[122:125], v[242:245], v[12:15]
	v_mfma_f32_16x16x32_bf16 v[16:19], v[146:149], v[242:245], v[16:19]
	v_mfma_f32_16x16x32_bf16 v[154:157], v[122:125], v[194:197], v[154:157]
	v_mfma_f32_16x16x32_bf16 v[158:161], v[146:149], v[194:197], v[158:161]
	v_mfma_f32_16x16x32_bf16 v[162:165], v[122:125], v[218:221], v[162:165]
	v_mfma_f32_16x16x32_bf16 v[166:169], v[146:149], v[218:221], v[166:169]
	v_mfma_f32_16x16x32_bf16 v[170:173], v[122:125], v[226:229], v[170:173]
	v_mfma_f32_16x16x32_bf16 v[174:177], v[146:149], v[226:229], v[174:177]
	s_setprio 0
	s_setprio 1
	v_mfma_f32_16x16x32_bf16 v[20:23], v[150:153], v[190:193], v[20:23]
	v_mfma_f32_16x16x32_bf16 v[32:35], v[182:185], v[190:193], v[32:35]
	v_mfma_f32_16x16x32_bf16 v[36:39], v[150:153], v[198:201], v[36:39]
	v_mfma_f32_16x16x32_bf16 v[60:63], v[182:185], v[198:201], v[60:63]
	v_mfma_f32_16x16x32_bf16 v[108:111], v[150:153], v[222:225], v[110:113]
	v_mfma_f32_16x16x32_bf16 v[112:115], v[182:185], v[222:225], v[114:117]
	v_mfma_f32_16x16x32_bf16 v[24:27], v[150:153], v[238:241], v[24:27]
	v_mfma_f32_16x16x32_bf16 v[28:31], v[182:185], v[238:241], v[28:31]
	v_mfma_f32_16x16x32_bf16 v[20:23], v[178:181], v[194:197], v[20:23]
	v_mfma_f32_16x16x32_bf16 v[32:35], v[186:189], v[194:197], v[32:35]
	v_mfma_f32_16x16x32_bf16 v[36:39], v[178:181], v[218:221], v[36:39]
	v_mfma_f32_16x16x32_bf16 v[60:63], v[186:189], v[218:221], v[60:63]
	v_mfma_f32_16x16x32_bf16 v[108:111], v[178:181], v[226:229], v[108:111]
	v_mfma_f32_16x16x32_bf16 v[112:115], v[186:189], v[226:229], v[112:115]
	v_mfma_f32_16x16x32_bf16 v[24:27], v[178:181], v[242:245], v[24:27]
	v_mfma_f32_16x16x32_bf16 v[28:31], v[186:189], v[242:245], v[28:31]
	s_setprio 0
	s_barrier
; #define PG8_STAGE(bufoff, gbase, voff) do { _Pragma("unroll") for (int _i = 0; _i < 2; ++_i) \
;         __builtin_amdgcn_global_load_lds((const unsigned*)((const char*)(gbase) + (voff)[_i]), (PG8_LAS unsigned*)(lds + (bufoff) + ldsw + _i * 8192), 16, 0, 0); } while (0)
; #define PG8_LDA(dst, b, h) do { _Pragma("unroll") for (int m = 0; m < 4; ++m) _Pragma("unroll") for (int k = 0; k < 2; ++k) dst[m][k] = *(const PG8_LAS bf16x8*)(lds + PG8_SA(b, h) + aoff + m * 2048 + k * 1024); } while (0)
; #define PG8_LDB(dst, b, h) do { _Pragma("unroll") for (int n = 0; n < 2; ++n) _Pragma("unroll") for (int k = 0; k < 2; ++k) dst[n][k] = *(const PG8_LAS bf16x8*)(lds + PG8_SB(b, h) + boff + n * 2048 + k * 1024); } while (0)
; #define PG8_MMA(ai, bj, At, Bt) do { __builtin_amdgcn_s_setprio(1); _Pragma("unroll") for (int m = 0; m < 4; ++m) _Pragma("unroll") for (int n = 0; n < 2; ++n) _Pragma("unroll") for (int k = 0; k < 2; ++k) \
;         acc[ai][bj][m][n] = __builtin_amdgcn_mfma_f32_16x16x32_bf16(Bt[n][k], At[m][k], acc[ai][bj][m][n], 0, 0, 0); __builtin_amdgcn_s_setprio(0); } while (0)
; #define PG8_WAIT_V(n) asm volatile("s_waitcnt vmcnt(" #n ")" ::: "memory")
; #define PG8_WAIT_L(n) asm volatile("s_waitcnt lgkmcnt(" #n ")" ::: "memory")
; #define PG8_BAR __builtin_amdgcn_s_barrier()
; #define PG8_SCHED __builtin_amdgcn_sched_barrier(0)
; template <class Epi, class Sched, bool ALIGN_EPI = false, bool SP2 = false>
; __device__ __forceinline__ void gemm_phase(PG8_LAS unsigned char* lds, const Gemm g, const Sched& S, const Epi& E, const int tid) {
;     ...
;             PG8_LDB(B0, 1, 0); PG8_LDB(B1, 1, 1); PG8_SCHED; PG8_LDA(At, 1, 0); PG8_STAGE(PG8_SA(0, 1), a2 + hstepA, voffA);
;             PG8_WAIT_V(8); PG8_WAIT_L(0); PG8_BAR; PG8_MMA(0, 0, At, B0); PG8_MMA(0, 1, At, B1); PG8_BAR; PG8_SCHED;
;             PG8_LDA(At, 1, 1); PG8_STAGE(PG8_SB(1, 0), b3, voffB); PG8_STAGE(PG8_SB(1, 1), b3 + hstepB, voffB); PG8_STAGE(PG8_SA(1, 0), a3, voffA);
;             PG8_WAIT_V(8); PG8_WAIT_L(0); PG8_BAR; PG8_MMA(1, 0, At, B0); PG8_MMA(1, 1, At, B1); PG8_BAR; PG8_SCHED;
	ds_read_b128 v[116:119], v10
	ds_read_b128 v[120:123], v10 offset:1024
	ds_read_b128 v[124:127], v10 offset:2048
	ds_read_b128 v[142:145], v10 offset:3072
	ds_read_b128 v[146:149], v11
	ds_read_b128 v[150:153], v11 offset:1024
	ds_read_b128 v[178:181], v11 offset:2048
	ds_read_b128 v[182:185], v11 offset:3072
	s_add_u32 s60, s18, 0x18200
	s_addc_u32 s61, s19, 0
	s_mov_b32 m0, s30
	v_lshl_add_u64 v[136:137], s[60:61], 0, v[134:135]
	ds_read_b128 v[186:189], v141 offset:32768
	ds_read_b128 v[190:193], v141 offset:33792
	ds_read_b128 v[194:197], v141 offset:34816
	ds_read_b128 v[198:201], v141 offset:35840
	ds_read_b128 v[218:221], v141 offset:36864
	ds_read_b128 v[222:225], v141 offset:37888
	ds_read_b128 v[226:229], v141 offset:38912
	ds_read_b128 v[238:241], v141 offset:39936
	global_load_lds_dwordx4 v[136:137], off nt
	v_lshl_add_u64 v[136:137], s[60:61], 0, v[130:131]
	s_mov_b32 m0, s31
	s_nop 0
	global_load_lds_dwordx4 v[136:137], off nt
	s_waitcnt vmcnt(8)
	s_waitcnt lgkmcnt(0)
	s_barrier
	s_setprio 1
	s_waitcnt lgkmcnt(0)
	v_mfma_f32_16x16x32_bf16 v[64:67], v[116:119], v[186:189], v[64:67]
	v_mfma_f32_16x16x32_bf16 v[68:71], v[124:127], v[186:189], v[68:71]
	v_mfma_f32_16x16x32_bf16 v[72:75], v[116:119], v[194:197], v[72:75]
	v_mfma_f32_16x16x32_bf16 v[76:79], v[124:127], v[194:197], v[76:79]
	v_mfma_f32_16x16x32_bf16 v[80:83], v[116:119], v[218:221], v[80:83]
	v_mfma_f32_16x16x32_bf16 v[84:87], v[124:127], v[218:221], v[84:87]
	v_mfma_f32_16x16x32_bf16 v[88:91], v[116:119], v[226:229], v[88:91]
	v_mfma_f32_16x16x32_bf16 v[92:95], v[124:127], v[226:229], v[92:95]
	v_mfma_f32_16x16x32_bf16 v[64:67], v[120:123], v[190:193], v[64:67]
	v_mfma_f32_16x16x32_bf16 v[68:71], v[142:145], v[190:193], v[68:71]
	v_mfma_f32_16x16x32_bf16 v[72:75], v[120:123], v[198:201], v[72:75]
	v_mfma_f32_16x16x32_bf16 v[76:79], v[142:145], v[198:201], v[76:79]
	v_mfma_f32_16x16x32_bf16 v[80:83], v[120:123], v[222:225], v[80:83]
	v_mfma_f32_16x16x32_bf16 v[84:87], v[142:145], v[222:225], v[84:87]
	v_mfma_f32_16x16x32_bf16 v[88:91], v[120:123], v[238:241], v[88:91]
	v_mfma_f32_16x16x32_bf16 v[92:95], v[142:145], v[238:241], v[92:95]
	s_setprio 0
	s_setprio 1
	v_mfma_f32_16x16x32_bf16 v[96:99], v[146:149], v[186:189], v[96:99]
	v_mfma_f32_16x16x32_bf16 v[100:103], v[178:181], v[186:189], v[100:103]
	v_mfma_f32_16x16x32_bf16 v[104:107], v[146:149], v[194:197], v[104:107]
	v_mfma_f32_16x16x32_bf16 v[40:43], v[178:181], v[194:197], v[40:43]
	v_mfma_f32_16x16x32_bf16 v[44:47], v[146:149], v[218:221], v[44:47]
	v_mfma_f32_16x16x32_bf16 v[48:51], v[178:181], v[218:221], v[48:51]
	v_mfma_f32_16x16x32_bf16 v[52:55], v[146:149], v[226:229], v[52:55]
	v_mfma_f32_16x16x32_bf16 v[56:59], v[178:181], v[226:229], v[56:59]
	v_mfma_f32_16x16x32_bf16 v[96:99], v[150:153], v[190:193], v[96:99]
	v_mfma_f32_16x16x32_bf16 v[100:103], v[182:185], v[190:193], v[100:103]
	v_mfma_f32_16x16x32_bf16 v[104:107], v[150:153], v[198:201], v[104:107]
	v_mfma_f32_16x16x32_bf16 v[40:43], v[182:185], v[198:201], v[40:43]
	v_mfma_f32_16x16x32_bf16 v[44:47], v[150:153], v[222:225], v[44:47]
	v_mfma_f32_16x16x32_bf16 v[48:51], v[182:185], v[222:225], v[48:51]
	v_mfma_f32_16x16x32_bf16 v[52:55], v[150:153], v[238:241], v[52:55]
	v_mfma_f32_16x16x32_bf16 v[56:59], v[182:185], v[238:241], v[56:59]
	s_setprio 0
	s_barrier
	s_mov_b32 m0, s59
	v_lshl_add_u64 v[0:1], v[0:1], 0, s[96:97]
	s_add_u32 s20, s20, 0x18280
	ds_read_b128 v[186:189], v141 offset:49152
	ds_read_b128 v[190:193], v141 offset:50176
	ds_read_b128 v[194:197], v141 offset:51200
	ds_read_b128 v[198:201], v141 offset:52224
	ds_read_b128 v[218:221], v141 offset:53248
	ds_read_b128 v[222:225], v141 offset:54272
	ds_read_b128 v[226:229], v141 offset:55296
	ds_read_b128 v[238:241], v141 offset:56320
	global_load_lds_dwordx4 v[0:1], off nt
	v_lshl_add_u64 v[0:1], v[2:3], 0, s[96:97]
	s_mov_b32 m0, s55
	s_addc_u32 s21, s21, 0
	global_load_lds_dwordx4 v[0:1], off nt
	v_lshl_add_u64 v[0:1], s[20:21], 0, v[132:133]
	s_mov_b32 m0, s56
	s_nop 0
	global_load_lds_dwordx4 v[0:1], off nt
	v_lshl_add_u64 v[0:1], s[20:21], 0, v[128:129]
	s_mov_b32 m0, s58
	s_nop 0
	global_load_lds_dwordx4 v[0:1], off nt
	v_lshl_add_u64 v[0:1], v[4:5], 0, s[96:97]
	s_mov_b32 m0, s35
	s_nop 0
	global_load_lds_dwordx4 v[0:1], off nt
	v_lshl_add_u64 v[0:1], v[6:7], 0, s[96:97]
	s_mov_b32 m0, s36
	s_nop 0
	global_load_lds_dwordx4 v[0:1], off nt
	s_waitcnt vmcnt(8)
	s_waitcnt lgkmcnt(0)
	s_barrier
	s_setprio 1
	s_waitcnt lgkmcnt(0)
	v_mfma_f32_16x16x32_bf16 v[0:3], v[116:119], v[186:189], v[154:157]
	v_mfma_f32_16x16x32_bf16 v[4:7], v[124:127], v[186:189], v[158:161]
	v_mfma_f32_16x16x32_bf16 v[12:15], v[116:119], v[226:229], v[12:15]
	v_mfma_f32_16x16x32_bf16 v[16:19], v[124:127], v[226:229], v[16:19]
	v_mfma_f32_16x16x32_bf16 v[0:3], v[120:123], v[190:193], v[0:3]
	v_mfma_f32_16x16x32_bf16 v[4:7], v[142:145], v[190:193], v[4:7]
	v_mfma_f32_16x16x32_bf16 v[154:157], v[116:119], v[194:197], v[162:165]
	v_mfma_f32_16x16x32_bf16 v[158:161], v[124:127], v[194:197], v[166:169]
	v_mfma_f32_16x16x32_bf16 v[162:165], v[116:119], v[218:221], v[170:173]
	v_mfma_f32_16x16x32_bf16 v[166:169], v[124:127], v[218:221], v[174:177]
	v_mfma_f32_16x16x32_bf16 v[12:15], v[120:123], v[238:241], v[12:15]
	v_mfma_f32_16x16x32_bf16 v[16:19], v[142:145], v[238:241], v[16:19]
	v_mfma_f32_16x16x32_bf16 v[154:157], v[120:123], v[198:201], v[154:157]
	v_mfma_f32_16x16x32_bf16 v[158:161], v[142:145], v[198:201], v[158:161]
	v_mfma_f32_16x16x32_bf16 v[162:165], v[120:123], v[222:225], v[162:165]
	v_mfma_f32_16x16x32_bf16 v[166:169], v[142:145], v[222:225], v[166:169]
	s_setprio 0
	s_setprio 1
	v_mfma_f32_16x16x32_bf16 v[20:23], v[146:149], v[186:189], v[20:23]
	v_mfma_f32_16x16x32_bf16 v[32:35], v[178:181], v[186:189], v[32:35]
	v_mfma_f32_16x16x32_bf16 v[36:39], v[146:149], v[194:197], v[36:39]
	v_mfma_f32_16x16x32_bf16 v[60:63], v[178:181], v[194:197], v[60:63]
	v_mfma_f32_16x16x32_bf16 v[108:111], v[146:149], v[218:221], v[108:111]
	v_mfma_f32_16x16x32_bf16 v[112:115], v[178:181], v[218:221], v[112:115]
	v_mfma_f32_16x16x32_bf16 v[24:27], v[146:149], v[226:229], v[24:27]
	v_mfma_f32_16x16x32_bf16 v[28:31], v[178:181], v[226:229], v[28:31]
	v_mfma_f32_16x16x32_bf16 v[20:23], v[150:153], v[190:193], v[20:23]
	v_mfma_f32_16x16x32_bf16 v[32:35], v[182:185], v[190:193], v[32:35]
	v_mfma_f32_16x16x32_bf16 v[36:39], v[150:153], v[198:201], v[36:39]
	v_mfma_f32_16x16x32_bf16 v[60:63], v[182:185], v[198:201], v[60:63]
	v_mfma_f32_16x16x32_bf16 v[108:111], v[150:153], v[222:225], v[108:111]
	v_mfma_f32_16x16x32_bf16 v[112:115], v[182:185], v[222:225], v[112:115]
	v_mfma_f32_16x16x32_bf16 v[24:27], v[150:153], v[238:241], v[24:27]
	v_mfma_f32_16x16x32_bf16 v[28:31], v[182:185], v[238:241], v[28:31]
	s_setprio 0
	s_barrier
; #define PG8_STAGE(bufoff, gbase, voff) do { _Pragma("unroll") for (int _i = 0; _i < 2; ++_i) \
;         __builtin_amdgcn_global_load_lds((const unsigned*)((const char*)(gbase) + (voff)[_i]), (PG8_LAS unsigned*)(lds + (bufoff) + ldsw + _i * 8192), 16, 0, 0); } while (0)
; #define PG8_LDA(dst, b, h) do { _Pragma("unroll") for (int m = 0; m < 4; ++m) _Pragma("unroll") for (int k = 0; k < 2; ++k) dst[m][k] = *(const PG8_LAS bf16x8*)(lds + PG8_SA(b, h) + aoff + m * 2048 + k * 1024); } while (0)
; #define PG8_LDB(dst, b, h) do { _Pragma("unroll") for (int n = 0; n < 2; ++n) _Pragma("unroll") for (int k = 0; k < 2; ++k) dst[n][k] = *(const PG8_LAS bf16x8*)(lds + PG8_SB(b, h) + boff + n * 2048 + k * 1024); } while (0)
; #define PG8_MMA(ai, bj, At, Bt) do { __builtin_amdgcn_s_setprio(1); _Pragma("unroll") for (int m = 0; m < 4; ++m) _Pragma("unroll") for (int n = 0; n < 2; ++n) _Pragma("unroll") for (int k = 0; k < 2; ++k) \
;         acc[ai][bj][m][n] = __builtin_amdgcn_mfma_f32_16x16x32_bf16(Bt[n][k], At[m][k], acc[ai][bj][m][n], 0, 0, 0); __builtin_amdgcn_s_setprio(0); } while (0)
; #define PG8_WAIT_V(n) asm volatile("s_waitcnt vmcnt(" #n ")" ::: "memory")
; #define PG8_WAIT_L(n) asm volatile("s_waitcnt lgkmcnt(" #n ")" ::: "memory")
; template <class Epi, class Sched, bool ALIGN_EPI = false, bool SP2 = false>
; __device__ __forceinline__ void gemm_phase(PG8_LAS unsigned char* lds, const Gemm g, const Sched& S, const Epi& E, const int tid) {
;     ...
;             const char* a2 = last ? nA : cA + (size_t)(t + 2) * kstep; const char* b2 = last ? nB : cB + (size_t)(t + 2) * kstep;
;             const char* a3 = a2 + kstep; const char* b3 = b2 + kstep;
;             if (last && has_next) S.a_ready(nxt);
;             if constexpr (SP2) {
;             PG8_LDB(B0, 0, 0); PG8_LDB(B1, 0, 1); PG8_SCHED; PG8_LDA(At, 0, 0); PG8_STAGE(PG8_SA(1, 1), a1 + hstepA, voffA);
;             PG8_WAIT_V(8); PG8_WAIT_L(0); PG8_BAR; PG8_MMA(0, 0, At, B0); PG8_MMA(0, 1, At, B1); PG8_BAR; PG8_SCHED;
;             PG8_LDA(At, 0, 1); PG8_STAGE(PG8_SB(0, 0), b2, voffB); PG8_STAGE(PG8_SB(0, 1), b2 + hstepB, voffB); PG8_STAGE(PG8_SA(0, 0), a2, voffA);
;             PG8_WAIT_V(8); PG8_WAIT_L(0); PG8_BAR; PG8_MMA(1, 0, At, B0); PG8_MMA(1, 1, At, B1); PG8_BAR; PG8_SCHED;
;             PG8_LDB(B0, 1, 0); PG8_LDB(B1, 1, 1); PG8_SCHED; PG8_LDA(At, 1, 0); PG8_STAGE(PG8_SA(0, 1), a2 + hstepA, voffA);
	ds_read_b128 v[116:119], v8
	ds_read_b128 v[120:123], v8 offset:1024
	ds_read_b128 v[124:127], v8 offset:2048
	ds_read_b128 v[142:145], v8 offset:3072
	ds_read_b128 v[146:149], v9
	ds_read_b128 v[150:153], v9 offset:1024
	ds_read_b128 v[170:173], v9 offset:2048
	ds_read_b128 v[174:177], v9 offset:3072
	s_add_u32 s18, s18, 0x18280
	s_addc_u32 s19, s19, 0
	s_mov_b32 m0, s57
	v_lshl_add_u64 v[8:9], s[18:19], 0, v[134:135]
	ds_read_b128 v[178:181], v141
	ds_read_b128 v[182:185], v141 offset:1024
	ds_read_b128 v[186:189], v141 offset:2048
	ds_read_b128 v[190:193], v141 offset:3072
	ds_read_b128 v[194:197], v141 offset:4096
	ds_read_b128 v[198:201], v141 offset:5120
	ds_read_b128 v[218:221], v141 offset:6144
	ds_read_b128 v[222:225], v141 offset:7168
	global_load_lds_dwordx4 v[8:9], off nt
	v_lshl_add_u64 v[8:9], s[18:19], 0, v[130:131]
	s_mov_b32 m0, s43
	s_nop 0
	global_load_lds_dwordx4 v[8:9], off nt
	s_waitcnt vmcnt(8)
	s_waitcnt lgkmcnt(0)
	s_barrier
	s_setprio 1
	s_waitcnt lgkmcnt(0)
	v_mfma_f32_16x16x32_bf16 v[64:67], v[116:119], v[178:181], v[64:67]
	v_mfma_f32_16x16x32_bf16 v[68:71], v[124:127], v[178:181], v[68:71]
	v_mfma_f32_16x16x32_bf16 v[72:75], v[116:119], v[186:189], v[72:75]
	v_mfma_f32_16x16x32_bf16 v[76:79], v[124:127], v[186:189], v[76:79]
	v_mfma_f32_16x16x32_bf16 v[80:83], v[116:119], v[194:197], v[80:83]
	v_mfma_f32_16x16x32_bf16 v[84:87], v[124:127], v[194:197], v[84:87]
	v_mfma_f32_16x16x32_bf16 v[88:91], v[116:119], v[218:221], v[88:91]
	v_mfma_f32_16x16x32_bf16 v[64:67], v[120:123], v[182:185], v[64:67]
	v_mfma_f32_16x16x32_bf16 v[68:71], v[142:145], v[182:185], v[68:71]
	v_mfma_f32_16x16x32_bf16 v[72:75], v[120:123], v[190:193], v[72:75]
	v_mfma_f32_16x16x32_bf16 v[76:79], v[142:145], v[190:193], v[76:79]
	v_mfma_f32_16x16x32_bf16 v[80:83], v[120:123], v[198:201], v[80:83]
	v_mfma_f32_16x16x32_bf16 v[84:87], v[142:145], v[198:201], v[84:87]
	v_mfma_f32_16x16x32_bf16 v[226:229], v[120:123], v[222:225], v[88:91]
	v_mfma_f32_16x16x32_bf16 v[88:91], v[124:127], v[218:221], v[92:95]
	v_mfma_f32_16x16x32_bf16 v[238:241], v[142:145], v[222:225], v[88:91]
	s_setprio 0
	s_setprio 1
	v_mfma_f32_16x16x32_bf16 v[88:91], v[146:149], v[178:181], v[96:99]
	v_mfma_f32_16x16x32_bf16 v[96:99], v[150:153], v[182:185], v[88:91]
	v_mfma_f32_16x16x32_bf16 v[88:91], v[170:173], v[178:181], v[100:103]
	v_mfma_f32_16x16x32_bf16 v[40:43], v[170:173], v[186:189], v[40:43]
	v_mfma_f32_16x16x32_bf16 v[44:47], v[146:149], v[194:197], v[44:47]
	v_mfma_f32_16x16x32_bf16 v[48:51], v[170:173], v[194:197], v[48:51]
	v_mfma_f32_16x16x32_bf16 v[52:55], v[146:149], v[218:221], v[52:55]
	v_mfma_f32_16x16x32_bf16 v[56:59], v[170:173], v[218:221], v[56:59]
	v_mfma_f32_16x16x32_bf16 v[100:103], v[174:177], v[182:185], v[88:91]
	v_mfma_f32_16x16x32_bf16 v[88:91], v[146:149], v[186:189], v[104:107]
	v_mfma_f32_16x16x32_bf16 v[40:43], v[174:177], v[190:193], v[40:43]
	v_mfma_f32_16x16x32_bf16 v[44:47], v[150:153], v[198:201], v[44:47]
	v_mfma_f32_16x16x32_bf16 v[48:51], v[174:177], v[198:201], v[48:51]
	v_mfma_f32_16x16x32_bf16 v[52:55], v[150:153], v[222:225], v[52:55]
	v_mfma_f32_16x16x32_bf16 v[56:59], v[174:177], v[222:225], v[56:59]
	v_mfma_f32_16x16x32_bf16 v[178:181], v[150:153], v[190:193], v[88:91]
	s_setprio 0
	s_barrier
	s_mov_b32 m0, s54
	v_lshl_add_u64 v[136:137], s[16:17], 0, v[132:133]
	s_add_u32 s18, s16, 0x18000
	ds_read_b128 v[88:91], v141 offset:16384
	ds_read_b128 v[92:95], v141 offset:17408
	ds_read_b128 v[104:107], v141 offset:18432
	ds_read_b128 v[182:185], v141 offset:19456
	ds_read_b128 v[186:189], v141 offset:20480
	ds_read_b128 v[190:193], v141 offset:21504
	ds_read_b128 v[194:197], v141 offset:22528
	ds_read_b128 v[198:201], v141 offset:23552
	global_load_lds_dwordx4 v[136:137], off nt
	v_lshl_add_u64 v[202:203], s[16:17], 0, v[128:129]
	s_mov_b32 m0, s47
	s_addc_u32 s19, s17, 0
	global_load_lds_dwordx4 v[202:203], off nt
	v_lshl_add_u64 v[8:9], s[18:19], 0, v[132:133]
	s_mov_b32 m0, s49
	v_lshl_add_u64 v[232:233], s[0:1], 0, v[134:135]
	global_load_lds_dwordx4 v[8:9], off nt
	v_lshl_add_u64 v[8:9], s[18:19], 0, v[128:129]
	s_mov_b32 m0, s50
	v_lshl_add_u64 v[210:211], s[0:1], 0, v[130:131]
	global_load_lds_dwordx4 v[8:9], off nt
	s_mov_b32 m0, s28
	s_nop 0
	global_load_lds_dwordx4 v[232:233], off nt
	s_mov_b32 m0, s29
	s_nop 0
	global_load_lds_dwordx4 v[210:211], off nt
	s_waitcnt vmcnt(8)
	s_waitcnt lgkmcnt(0)
	s_barrier
	s_setprio 1
	s_waitcnt lgkmcnt(0)
	v_mfma_f32_16x16x32_bf16 v[0:3], v[116:119], v[88:91], v[0:3]
	v_mfma_f32_16x16x32_bf16 v[4:7], v[124:127], v[88:91], v[4:7]
	v_mfma_f32_16x16x32_bf16 v[12:15], v[116:119], v[194:197], v[12:15]
	v_mfma_f32_16x16x32_bf16 v[16:19], v[124:127], v[194:197], v[16:19]
	v_mfma_f32_16x16x32_bf16 v[0:3], v[120:123], v[92:95], v[0:3]
	v_mfma_f32_16x16x32_bf16 v[4:7], v[142:145], v[92:95], v[4:7]
	v_mfma_f32_16x16x32_bf16 v[154:157], v[116:119], v[104:107], v[154:157]
	v_mfma_f32_16x16x32_bf16 v[158:161], v[124:127], v[104:107], v[158:161]
	v_mfma_f32_16x16x32_bf16 v[162:165], v[116:119], v[186:189], v[162:165]
	v_mfma_f32_16x16x32_bf16 v[166:169], v[124:127], v[186:189], v[166:169]
	v_mfma_f32_16x16x32_bf16 v[12:15], v[120:123], v[198:201], v[12:15]
	v_mfma_f32_16x16x32_bf16 v[16:19], v[142:145], v[198:201], v[16:19]
	v_mfma_f32_16x16x32_bf16 v[154:157], v[120:123], v[182:185], v[154:157]
	v_mfma_f32_16x16x32_bf16 v[158:161], v[142:145], v[182:185], v[158:161]
	v_mfma_f32_16x16x32_bf16 v[162:165], v[120:123], v[190:193], v[162:165]
	v_mfma_f32_16x16x32_bf16 v[166:169], v[142:145], v[190:193], v[166:169]
	s_setprio 0
	s_setprio 1
	v_mfma_f32_16x16x32_bf16 v[60:63], v[170:173], v[104:107], v[60:63]
	v_mfma_f32_16x16x32_bf16 v[20:23], v[146:149], v[88:91], v[20:23]
	v_mfma_f32_16x16x32_bf16 v[32:35], v[170:173], v[88:91], v[32:35]
	v_mfma_f32_16x16x32_bf16 v[36:39], v[146:149], v[104:107], v[36:39]
	v_mfma_f32_16x16x32_bf16 v[142:145], v[174:177], v[182:185], v[60:63]
	v_mfma_f32_16x16x32_bf16 v[60:63], v[146:149], v[186:189], v[108:111]
	v_mfma_f32_16x16x32_bf16 v[24:27], v[146:149], v[194:197], v[24:27]
	v_mfma_f32_16x16x32_bf16 v[20:23], v[150:153], v[92:95], v[20:23]
	v_mfma_f32_16x16x32_bf16 v[32:35], v[174:177], v[92:95], v[32:35]
	v_mfma_f32_16x16x32_bf16 v[36:39], v[150:153], v[182:185], v[36:39]
	v_mfma_f32_16x16x32_bf16 v[182:185], v[150:153], v[190:193], v[60:63]
	v_mfma_f32_16x16x32_bf16 v[60:63], v[170:173], v[186:189], v[112:115]
	v_mfma_f32_16x16x32_bf16 v[146:149], v[150:153], v[198:201], v[24:27]
	v_mfma_f32_16x16x32_bf16 v[24:27], v[170:173], v[194:197], v[28:31]
	v_mfma_f32_16x16x32_bf16 v[186:189], v[174:177], v[190:193], v[60:63]
	v_mfma_f32_16x16x32_bf16 v[150:153], v[174:177], v[198:201], v[24:27]
	s_setprio 0
	s_barrier
; #define PG8_STAGE(bufoff, gbase, voff) do { _Pragma("unroll") for (int _i = 0; _i < 2; ++_i) \
;         __builtin_amdgcn_global_load_lds((const unsigned*)((const char*)(gbase) + (voff)[_i]), (PG8_LAS unsigned*)(lds + (bufoff) + ldsw + _i * 8192), 16, 0, 0); } while (0)
; #define PG8_LDA(dst, b, h) do { _Pragma("unroll") for (int m = 0; m < 4; ++m) _Pragma("unroll") for (int k = 0; k < 2; ++k) dst[m][k] = *(const PG8_LAS bf16x8*)(lds + PG8_SA(b, h) + aoff + m * 2048 + k * 1024); } while (0)
; #define PG8_LDB(dst, b, h) do { _Pragma("unroll") for (int n = 0; n < 2; ++n) _Pragma("unroll") for (int k = 0; k < 2; ++k) dst[n][k] = *(const PG8_LAS bf16x8*)(lds + PG8_SB(b, h) + boff + n * 2048 + k * 1024); } while (0)
; #define PG8_MMA(ai, bj, At, Bt) do { __builtin_amdgcn_s_setprio(1); _Pragma("unroll") for (int m = 0; m < 4; ++m) _Pragma("unroll") for (int n = 0; n < 2; ++n) _Pragma("unroll") for (int k = 0; k < 2; ++k) \
;         acc[ai][bj][m][n] = __builtin_amdgcn_mfma_f32_16x16x32_bf16(Bt[n][k], At[m][k], acc[ai][bj][m][n], 0, 0, 0); __builtin_amdgcn_s_setprio(0); } while (0)
; #define PG8_WAIT_V(n) asm volatile("s_waitcnt vmcnt(" #n ")" ::: "memory")
; #define PG8_WAIT_L(n) asm volatile("s_waitcnt lgkmcnt(" #n ")" ::: "memory")
; #define PG8_BAR __builtin_amdgcn_s_barrier()
; #define PG8_SCHED __builtin_amdgcn_sched_barrier(0)
; template <class Epi, class Sched, bool ALIGN_EPI = false, bool SP2 = false>
; __device__ __forceinline__ void gemm_phase(PG8_LAS unsigned char* lds, const Gemm g, const Sched& S, const Epi& E, const int tid) {
;     ...
;             PG8_LDB(B0, 1, 0); PG8_LDB(B1, 1, 1); PG8_SCHED; PG8_LDA(At, 1, 0); PG8_STAGE(PG8_SA(0, 1), a2 + hstepA, voffA);
;             PG8_WAIT_V(8); PG8_WAIT_L(0); PG8_BAR; PG8_MMA(0, 0, At, B0); PG8_MMA(0, 1, At, B1); PG8_BAR; PG8_SCHED;
;             PG8_LDA(At, 1, 1); PG8_STAGE(PG8_SB(1, 0), b3, voffB); PG8_STAGE(PG8_SB(1, 1), b3 + hstepB, voffB); PG8_STAGE(PG8_SA(1, 0), a3, voffA);
;             PG8_WAIT_V(8); PG8_WAIT_L(0); PG8_BAR; PG8_MMA(1, 0, At, B0); PG8_MMA(1, 1, At, B1); PG8_BAR; PG8_SCHED;
;     ...
;         if constexpr (ALIGN_EPI) { if (wr == 0) PG8_BAR; }
	ds_read_b128 v[170:173], v10
	ds_read_b128 v[174:177], v10 offset:1024
	ds_read_b128 v[190:193], v10 offset:2048
	ds_read_b128 v[194:197], v10 offset:3072
	ds_read_b128 v[198:201], v11
	ds_read_b128 v[218:221], v11 offset:1024
	ds_read_b128 v[222:225], v11 offset:2048
	ds_read_b128 v[242:245], v11 offset:3072
	s_add_u32 s18, s0, 0x18000
	s_addc_u32 s19, s1, 0
	s_mov_b32 m0, s30
	v_lshl_add_u64 v[88:89], s[18:19], 0, v[134:135]
	ds_read_b128 v[8:11], v141 offset:32768
	ds_read_b128 v[24:27], v141 offset:33792
	ds_read_b128 v[28:31], v141 offset:34816
	ds_read_b128 v[60:63], v141 offset:35840
	ds_read_b128 v[246:249], v141 offset:36864
	ds_read_b128 v[250:253], v141 offset:37888
	ds_read_b128 v[206:209], v141 offset:38912
	ds_read_b128 v[214:217], v141 offset:39936
	global_load_lds_dwordx4 v[88:89], off nt
	v_lshl_add_u64 v[88:89], s[18:19], 0, v[130:131]
	s_mov_b32 m0, s31
	s_nop 0
	global_load_lds_dwordx4 v[88:89], off nt
	s_waitcnt vmcnt(8)
	s_waitcnt lgkmcnt(0)
	s_barrier
	s_setprio 1
	s_waitcnt lgkmcnt(0)
	v_mfma_f32_16x16x32_bf16 v[64:67], v[170:173], v[8:11], v[64:67]
	v_mfma_f32_16x16x32_bf16 v[124:127], v[174:177], v[24:27], v[64:67]
	v_mfma_f32_16x16x32_bf16 v[64:67], v[190:193], v[8:11], v[68:71]
	v_mfma_f32_16x16x32_bf16 v[120:123], v[194:197], v[24:27], v[64:67]
	v_mfma_f32_16x16x32_bf16 v[64:67], v[170:173], v[28:31], v[72:75]
	v_mfma_f32_16x16x32_bf16 v[108:111], v[174:177], v[60:63], v[64:67]
	v_mfma_f32_16x16x32_bf16 v[64:67], v[190:193], v[28:31], v[76:79]
	v_mfma_f32_16x16x32_bf16 v[104:107], v[194:197], v[60:63], v[64:67]
	v_mfma_f32_16x16x32_bf16 v[64:67], v[170:173], v[246:249], v[80:83]
	v_mfma_f32_16x16x32_bf16 v[92:95], v[174:177], v[250:253], v[64:67]
	v_mfma_f32_16x16x32_bf16 v[64:67], v[190:193], v[246:249], v[84:87]
	v_mfma_f32_16x16x32_bf16 v[88:91], v[194:197], v[250:253], v[64:67]
	v_mfma_f32_16x16x32_bf16 v[64:67], v[170:173], v[206:209], v[226:229]
	v_mfma_f32_16x16x32_bf16 v[76:79], v[174:177], v[214:217], v[64:67]
	v_mfma_f32_16x16x32_bf16 v[64:67], v[190:193], v[206:209], v[238:241]
	v_mfma_f32_16x16x32_bf16 v[72:75], v[194:197], v[214:217], v[64:67]
	s_setprio 0
	s_setprio 1
	v_mfma_f32_16x16x32_bf16 v[64:67], v[198:201], v[8:11], v[96:99]
	v_mfma_f32_16x16x32_bf16 v[8:11], v[222:225], v[8:11], v[100:103]
	v_mfma_f32_16x16x32_bf16 v[112:115], v[242:245], v[24:27], v[8:11]
	v_mfma_f32_16x16x32_bf16 v[8:11], v[198:201], v[28:31], v[178:181]
	v_mfma_f32_16x16x32_bf16 v[100:103], v[218:221], v[60:63], v[8:11]
	v_mfma_f32_16x16x32_bf16 v[8:11], v[222:225], v[28:31], v[40:43]
	v_mfma_f32_16x16x32_bf16 v[96:99], v[242:245], v[60:63], v[8:11]
	v_mfma_f32_16x16x32_bf16 v[8:11], v[198:201], v[246:249], v[44:47]
	v_mfma_f32_16x16x32_bf16 v[84:87], v[218:221], v[250:253], v[8:11]
	v_mfma_f32_16x16x32_bf16 v[8:11], v[222:225], v[246:249], v[48:51]
	v_mfma_f32_16x16x32_bf16 v[80:83], v[242:245], v[250:253], v[8:11]
	v_mfma_f32_16x16x32_bf16 v[8:11], v[198:201], v[206:209], v[52:55]
	v_mfma_f32_16x16x32_bf16 v[68:71], v[218:221], v[214:217], v[8:11]
	v_mfma_f32_16x16x32_bf16 v[8:11], v[222:225], v[206:209], v[56:59]
	v_mfma_f32_16x16x32_bf16 v[116:119], v[218:221], v[24:27], v[64:67]
	v_mfma_f32_16x16x32_bf16 v[64:67], v[242:245], v[214:217], v[8:11]
	s_setprio 0
	s_barrier
	s_mov_b32 m0, s59
	s_nop 2
	v_lshl_add_u64 v[8:9], v[136:137], 0, s[82:83]
	s_add_u32 s18, s16, 0x18080
	ds_read_b128 v[48:51], v141 offset:49152
	ds_read_b128 v[178:181], v141 offset:50176
	ds_read_b128 v[206:209], v141 offset:51200
	ds_read_b128 v[214:217], v141 offset:52224
	ds_read_b128 v[226:229], v141 offset:53248
	ds_read_b128 v[238:241], v141 offset:54272
	ds_read_b128 v[246:249], v141 offset:55296
	ds_read_b128 v[250:253], v141 offset:56320
	global_load_lds_dwordx4 v[8:9], off nt
	v_lshl_add_u64 v[8:9], v[202:203], 0, s[82:83]
	s_mov_b32 m0, s55
	s_addc_u32 s19, s17, 0
	global_load_lds_dwordx4 v[8:9], off nt
	v_lshl_add_u64 v[8:9], s[18:19], 0, v[132:133]
	s_mov_b32 m0, s56
	s_nop 0
	global_load_lds_dwordx4 v[8:9], off nt
	v_lshl_add_u64 v[8:9], s[18:19], 0, v[128:129]
	s_mov_b32 m0, s58
	s_nop 0
	global_load_lds_dwordx4 v[8:9], off nt
	v_lshl_add_u64 v[8:9], v[232:233], 0, s[82:83]
	s_mov_b32 m0, s35
	s_nop 0
	global_load_lds_dwordx4 v[8:9], off nt
	v_lshl_add_u64 v[8:9], v[210:211], 0, s[82:83]
	s_mov_b32 m0, s36
	s_nop 0
	global_load_lds_dwordx4 v[8:9], off nt
	s_waitcnt vmcnt(8)
	s_waitcnt lgkmcnt(0)
	s_barrier
	s_setprio 1
	s_waitcnt lgkmcnt(0)
	v_mfma_f32_16x16x32_bf16 v[0:3], v[170:173], v[48:51], v[0:3]
	v_mfma_f32_16x16x32_bf16 v[60:63], v[174:177], v[178:181], v[0:3]
	v_mfma_f32_16x16x32_bf16 v[0:3], v[190:193], v[48:51], v[4:7]
	v_mfma_f32_16x16x32_bf16 v[56:59], v[194:197], v[178:181], v[0:3]
	v_mfma_f32_16x16x32_bf16 v[0:3], v[170:173], v[206:209], v[154:157]
	v_mfma_f32_16x16x32_bf16 v[44:47], v[174:177], v[214:217], v[0:3]
	v_mfma_f32_16x16x32_bf16 v[0:3], v[190:193], v[206:209], v[158:161]
	v_mfma_f32_16x16x32_bf16 v[40:43], v[194:197], v[214:217], v[0:3]
	v_mfma_f32_16x16x32_bf16 v[0:3], v[170:173], v[226:229], v[162:165]
	v_mfma_f32_16x16x32_bf16 v[28:31], v[174:177], v[238:241], v[0:3]
	v_mfma_f32_16x16x32_bf16 v[0:3], v[190:193], v[226:229], v[166:169]
	v_mfma_f32_16x16x32_bf16 v[24:27], v[194:197], v[238:241], v[0:3]
	v_mfma_f32_16x16x32_bf16 v[0:3], v[170:173], v[246:249], v[12:15]
	v_mfma_f32_16x16x32_bf16 v[12:15], v[174:177], v[250:253], v[0:3]
	v_mfma_f32_16x16x32_bf16 v[0:3], v[190:193], v[246:249], v[16:19]
	v_mfma_f32_16x16x32_bf16 v[8:11], v[194:197], v[250:253], v[0:3]
	s_setprio 0
	s_setprio 1
	v_mfma_f32_16x16x32_bf16 v[0:3], v[198:201], v[48:51], v[20:23]
	v_mfma_f32_16x16x32_bf16 v[52:55], v[218:221], v[178:181], v[0:3]
	v_mfma_f32_16x16x32_bf16 v[0:3], v[222:225], v[48:51], v[32:35]
	v_mfma_f32_16x16x32_bf16 v[48:51], v[242:245], v[178:181], v[0:3]
	v_mfma_f32_16x16x32_bf16 v[0:3], v[198:201], v[206:209], v[36:39]
	v_mfma_f32_16x16x32_bf16 v[36:39], v[218:221], v[214:217], v[0:3]
	v_mfma_f32_16x16x32_bf16 v[0:3], v[222:225], v[206:209], v[142:145]
	v_mfma_f32_16x16x32_bf16 v[32:35], v[242:245], v[214:217], v[0:3]
	v_mfma_f32_16x16x32_bf16 v[0:3], v[198:201], v[226:229], v[182:185]
	v_mfma_f32_16x16x32_bf16 v[20:23], v[218:221], v[238:241], v[0:3]
	v_mfma_f32_16x16x32_bf16 v[0:3], v[222:225], v[226:229], v[186:189]
	v_mfma_f32_16x16x32_bf16 v[16:19], v[242:245], v[238:241], v[0:3]
	v_mfma_f32_16x16x32_bf16 v[0:3], v[198:201], v[246:249], v[146:149]
	v_mfma_f32_16x16x32_bf16 v[4:7], v[218:221], v[250:253], v[0:3]
	v_mfma_f32_16x16x32_bf16 v[0:3], v[222:225], v[246:249], v[150:153]
	v_mfma_f32_16x16x32_bf16 v[0:3], v[242:245], v[250:253], v[0:3]
	s_setprio 0
	s_barrier
	s_andn2_b64 vcc, exec, s[12:13]
	s_cbranch_vccnz .LBB0_328
	s_barrier
